# phase 0 rows loop: transposing butterfly rebuilt level by level (8/4/2/1 bpermutes in flight instead of one at a time)
# baseline (speedup 1.0000x reference)
; __device__ __forceinline__ unsigned cvt_pk_bf16(float lo, float hi) { unsigned r; asm volatile("v_cvt_pk_bf16_f32 %0, %1, %2" : "=v"(r) : "v"(lo), "v"(hi)); return r; }
; __device__ void phase0(const Params& P, LAS unsigned char* lds, const int G, const int bid) {
;     ...
;       for (int row0 = bid * 8 + wid; row0 < NTOK; row0 += G * 8 * 4) {
;           f32x4 vv[4][4];
; #pragma unroll
;           for (int rr = 0; rr < 4; ++rr) { const int row = row0 + rr * G * 8; const float* xr = xrow(P, row < NTOK ? row : row0);
; #pragma unroll
;               for (int i = 0; i < 4; ++i) vv[rr][i] = __builtin_nontemporal_load((const f32x4*)(xr + 4 * lane + 256 * i)); }
; #pragma unroll
;           for (int rr = 0; rr < 4; ++rr) { const int row = row0 + rr * G * 8; if (row >= NTOK) continue;
;               f32x4 (&v)[4] = vv[rr]; float ss = 0.f;
; #pragma unroll
;               for (int i = 0; i < 4; ++i)
; #pragma unroll
;                   for (int j = 0; j < 4; ++j) ss += v[i][j] * v[i][j];
; #pragma unroll
;               for (int o = 32; o >= 1; o >>= 1) ss += __shfl_xor(ss, o);
;               const float rstd = rsqrtf(ss * (1.0f / DM) + 1e-6f);
;               float ga[16];
; #pragma unroll
;               for (int c = 0; c < 16; ++c) ga[c] = 0.f;
; #pragma unroll
;               for (int i = 0; i < 4; ++i) { v[i] = v[i] * rstd * w4[i];
;                   u32x2 w; w.x = cvt_pk_bf16(v[i][0], v[i][1]); w.y = cvt_pk_bf16(v[i][2], v[i][3]);
;                   *(u32x2*)(abf + (size_t)row * DM + 4 * lane + 256 * i) = w;
.LBB0_1046:
	v_readlane_b32 s60, v254, 34
	v_ashrrev_i32_e32 v89, 31, v88
	v_readlane_b32 s61, v254, 35
	v_readlane_b32 s62, v254, 36
	v_readlane_b32 s63, v254, 37
	v_cmp_gt_i32_e64 s[50:51], s14, v88
	s_waitcnt vmcnt(4)
	v_add_u32_e32 v20, 0xffffc000, v88
	v_mov_b32_e32 v28, s63
	v_mov_b32_e32 v29, s61
	v_mov_b32_e32 v30, s62
	v_mov_b32_e32 v31, s60
	v_cndmask_b32_e64 v21, 0, v89, s[50:51]
	v_cndmask_b32_e64 v20, v20, v88, s[50:51]
	s_waitcnt lgkmcnt(0)
	v_cndmask_b32_e64 v19, v28, v29, s[50:51]
	v_cndmask_b32_e64 v18, v30, v31, s[50:51]
	v_lshlrev_b64 v[20:21], 12, v[20:21]
	v_lshl_add_u64 v[18:19], v[18:19], 0, v[20:21]
	v_lshl_add_u64 v[18:19], v[18:19], 0, v[0:1]
	global_load_dwordx4 v[92:95], v[18:19], off nt
	global_load_dwordx4 v[66:69], v[18:19], off offset:3072 nt
	global_load_dwordx4 v[74:77], v[18:19], off offset:1024 nt
	global_load_dwordx4 v[70:73], v[18:19], off offset:2048 nt
	v_add_u32_e32 v82, s0, v88
	v_add_u32_e32 v86, s10, v88
	v_cmp_gt_i32_e64 s[50:51], s15, v82
	v_add_u32_e32 v84, s11, v88
	v_readlane_b32 s64, v254, 38
	v_cndmask_b32_e64 v18, v88, v82, s[50:51]
	v_cmp_gt_i32_e64 s[50:51], s15, v86
	v_add_u32_e32 v20, 0xffffc000, v18
	v_ashrrev_i32_e32 v19, 31, v18
	v_cndmask_b32_e64 v22, v88, v86, s[50:51]
	v_cmp_gt_i32_e64 s[50:51], s15, v84
	v_add_u32_e32 v24, 0xffffc000, v22
	v_ashrrev_i32_e32 v23, 31, v22
	v_cndmask_b32_e64 v32, v88, v84, s[50:51]
	v_cmp_gt_i32_e64 s[50:51], s14, v18
	v_ashrrev_i32_e32 v34, 31, v32
	v_add_u32_e32 v33, 0xffffc000, v32
	v_cndmask_b32_e64 v19, 0, v19, s[50:51]
	v_cndmask_b32_e64 v18, v20, v18, s[50:51]
	v_cndmask_b32_e64 v21, v28, v29, s[50:51]
	v_cndmask_b32_e64 v20, v30, v31, s[50:51]
	v_cmp_gt_i32_e64 s[50:51], s14, v22
	v_lshlrev_b64 v[18:19], 12, v[18:19]
	v_lshl_add_u64 v[18:19], v[20:21], 0, v[18:19]
	v_cndmask_b32_e64 v22, v24, v22, s[50:51]
	v_cndmask_b32_e64 v23, 0, v23, s[50:51]
	v_lshlrev_b64 v[22:23], 12, v[22:23]
	v_lshl_add_u64 v[18:19], v[18:19], 0, v[0:1]
	global_load_dwordx4 v[62:65], v[18:19], off nt
	global_load_dwordx4 v[58:61], v[18:19], off offset:1024 nt
	global_load_dwordx4 v[54:57], v[18:19], off offset:2048 nt
	global_load_dwordx4 v[50:53], v[18:19], off offset:3072 nt
	v_readlane_b32 s65, v254, 39
	v_readlane_b32 s66, v254, 40
	v_readlane_b32 s67, v254, 41
	v_readlane_b32 s68, v254, 42
	v_readlane_b32 s69, v254, 43
	v_readlane_b32 s70, v254, 44
	v_readlane_b32 s71, v254, 45
	v_readlane_b32 s72, v254, 46
	v_readlane_b32 s73, v254, 47
	v_readlane_b32 s74, v254, 48
	v_readlane_b32 s75, v254, 49
	s_waitcnt vmcnt(7)
	v_mul_f32_e32 v35, v93, v93
	v_fmac_f32_e32 v35, v92, v92
	v_fmac_f32_e32 v35, v94, v94
	v_fmac_f32_e32 v35, v95, v95
	s_waitcnt vmcnt(5)
	v_fmac_f32_e32 v35, v74, v74
	v_fmac_f32_e32 v35, v75, v75
	v_fmac_f32_e32 v35, v76, v76
	v_fmac_f32_e32 v35, v77, v77
	s_waitcnt vmcnt(4)
	v_fmac_f32_e32 v35, v70, v70
	v_fmac_f32_e32 v35, v71, v71
	v_fmac_f32_e32 v35, v72, v72
	v_pk_mul_f32 v[26:27], v[66:67], v[66:67]
	v_fmac_f32_e32 v35, v73, v73
	v_add_f32_e32 v26, v26, v35
	v_pk_mul_f32 v[24:25], v[68:69], v[68:69]
	v_add_f32_e32 v26, v27, v26
	v_add_f32_e32 v24, v24, v26
	v_add_f32_e32 v26, v25, v24
	ds_bpermute_b32 v35, v96, v26
	v_cndmask_b32_e64 v25, v28, v29, s[50:51]
	v_cndmask_b32_e64 v24, v30, v31, s[50:51]
	v_cmp_gt_i32_e64 s[50:51], s14, v32
	v_lshl_add_u64 v[20:21], v[24:25], 0, v[22:23]
	v_lshl_add_u64 v[20:21], v[20:21], 0, v[0:1]
	v_cndmask_b32_e64 v27, 0, v34, s[50:51]
	s_waitcnt lgkmcnt(0)
	v_add_f32_e32 v34, v26, v35
	ds_bpermute_b32 v35, v97, v34
	v_cndmask_b32_e64 v29, v28, v29, s[50:51]
	v_cndmask_b32_e64 v28, v30, v31, s[50:51]
	v_cndmask_b32_e64 v26, v33, v32, s[50:51]
	v_lshlrev_b64 v[26:27], 12, v[26:27]
	s_waitcnt lgkmcnt(0)
	v_add_f32_e32 v30, v34, v35
	ds_bpermute_b32 v31, v98, v30
	v_lshl_add_u64 v[22:23], v[28:29], 0, v[26:27]
	v_lshl_add_u64 v[116:117], v[22:23], 0, v[0:1]
	global_load_dwordx4 v[46:49], v[20:21], off nt
	global_load_dwordx4 v[42:45], v[20:21], off offset:1024 nt
	global_load_dwordx4 v[38:41], v[20:21], off offset:2048 nt
	global_load_dwordx4 v[34:37], v[20:21], off offset:3072 nt
	s_waitcnt lgkmcnt(0)
	v_add_f32_e32 v24, v30, v31
	ds_bpermute_b32 v25, v99, v24
	s_waitcnt lgkmcnt(0)
	v_add_f32_e32 v22, v24, v25
	ds_bpermute_b32 v23, v100, v22
	s_waitcnt lgkmcnt(0)
	v_add_f32_e32 v18, v22, v23
	ds_bpermute_b32 v19, v101, v18
	s_waitcnt lgkmcnt(0)
	v_add_f32_e32 v18, v18, v19
	v_fmamk_f32 v18, v18, 0x3a800000, v210
	v_mul_f32_e32 v19, 0x4b800000, v18
	v_cmp_gt_f32_e64 s[50:51], s30, v18
	s_nop 1
	v_cndmask_b32_e64 v18, v18, v19, s[50:51]
	v_rsq_f32_e32 v83, v18
	global_load_dwordx4 v[30:33], v[116:117], off nt
	global_load_dwordx4 v[26:29], v[116:117], off offset:1024 nt
	global_load_dwordx4 v[22:25], v[116:117], off offset:2048 nt
	global_load_dwordx4 v[18:21], v[116:117], off offset:3072 nt
	v_mul_f32_e32 v85, 0x45800000, v83
	v_cndmask_b32_e64 v90, v83, v85, s[50:51]
	v_pk_mul_f32 v[116:117], v[92:93], v[90:91] op_sel_hi:[1,0]
	v_pk_mul_f32 v[92:93], v[94:95], v[90:91] op_sel_hi:[1,0]
	v_pk_mul_f32 v[138:139], v[2:3], v[116:117]
	v_pk_mul_f32 v[92:93], v[4:5], v[92:93]
	v_cvt_pk_bf16_f32 v94, v138, v139
	v_pk_mul_f32 v[74:75], v[74:75], v[90:91] op_sel_hi:[1,0]
	v_cvt_pk_bf16_f32 v95, v92, v93
	ds_read_b128 v[140:143], v102 offset:40960
	ds_read_b128 v[144:147], v102 offset:40976
	ds_read_b128 v[148:151], v102 offset:61440
	ds_read_b128 v[152:155], v102 offset:61456
	ds_read_b128 v[156:159], v102 offset:40992
	ds_read_b128 v[170:173], v102 offset:41008
	ds_read_b128 v[174:177], v102 offset:61472
	ds_read_b128 v[178:181], v102 offset:61488
	ds_read_b128 v[182:185], v103 offset:40960
	ds_read_b128 v[188:191], v103 offset:40976
	ds_read_b128 v[192:195], v103 offset:40992
	ds_read_b128 v[196:199], v103 offset:41008
	v_pk_mul_f32 v[76:77], v[76:77], v[90:91] op_sel_hi:[1,0]
	v_pk_mul_f32 v[70:71], v[70:71], v[90:91] op_sel_hi:[1,0]
	s_waitcnt lgkmcnt(11)
; #define LAS __attribute__((address_space(3)))
; __device__ __forceinline__ unsigned cvt_pk_bf16(float lo, float hi) { unsigned r; asm volatile("v_cvt_pk_bf16_f32 %0, %1, %2" : "=v"(r) : "v"(lo), "v"(hi)); return r; }
; __device__ void phase0(const Params& P, LAS unsigned char* lds, const int G, const int bid) {
;     ...
;               for (int i = 0; i < 4; ++i) { v[i] = v[i] * rstd * w4[i];
;                   u32x2 w; w.x = cvt_pk_bf16(v[i][0], v[i][1]); w.y = cvt_pk_bf16(v[i][2], v[i][3]);
;                   *(u32x2*)(abf + (size_t)row * DM + 4 * lane + 256 * i) = w;
; #pragma unroll
;                   for (int j = 0; j < 4; ++j) { const LAS float* wr_ = wg + (j * 256 + i * 64 + lane) * 20; const float a = v[i][j];
; #pragma unroll
;                       for (int q = 0; q < 4; ++q) { const f32x4 wv = *(const LAS f32x4*)(wr_ + 4 * q);
;                           ga[4 * q] += a * wv[0]; ga[4 * q + 1] += a * wv[1]; ga[4 * q + 2] += a * wv[2]; ga[4 * q + 3] += a * wv[3]; } } }
	v_fma_f32 v87, v141, v138, 0
	v_fma_f32 v85, v142, v138, 0
	v_fma_f32 v83, v143, v138, 0
	s_waitcnt lgkmcnt(10)
	v_fma_f32 v120, v144, v138, 0
	v_fma_f32 v119, v145, v138, 0
	v_fma_f32 v118, v146, v138, 0
	v_fma_f32 v117, v147, v138, 0
	s_waitcnt lgkmcnt(9)
	v_fmac_f32_e32 v85, v150, v139
	v_fmac_f32_e32 v83, v151, v139
	s_waitcnt lgkmcnt(8)
	v_fmac_f32_e32 v120, v152, v139
	v_fmac_f32_e32 v119, v153, v139
	v_fmac_f32_e32 v118, v154, v139
	v_fmac_f32_e32 v117, v155, v139
	ds_read_b128 v[222:225], v103 offset:61440
	ds_read_b128 v[226:229], v103 offset:61456
	v_fmac_f32_e32 v87, v149, v139
	v_fma_f32 v116, v140, v138, 0
	v_fmac_f32_e32 v116, v148, v139
	s_waitcnt lgkmcnt(9)
	v_fma_f32 v125, v156, v138, 0
	v_fma_f32 v123, v157, v138, 0
	v_fma_f32 v122, v158, v138, 0
	v_fma_f32 v121, v159, v138, 0
	ds_read_b128 v[230:233], v103 offset:61472
	ds_read_b128 v[234:237], v103 offset:61488
	s_waitcnt lgkmcnt(10)
	v_fma_f32 v124, v173, v138, 0
	v_pk_mul_f32 v[76:77], v[8:9], v[76:77]
	v_pk_mul_f32 v[72:73], v[72:73], v[90:91] op_sel_hi:[1,0]
	s_waitcnt lgkmcnt(9)
	v_fmac_f32_e32 v125, v174, v139
	v_fmac_f32_e32 v123, v175, v139
	v_fmac_f32_e32 v122, v176, v139
	v_fma_f32 v128, v170, v138, 0
	v_fma_f32 v127, v171, v138, 0
	v_fma_f32 v126, v172, v138, 0
	s_waitcnt lgkmcnt(8)
	v_fmac_f32_e32 v128, v178, v139
	v_fmac_f32_e32 v127, v179, v139
	v_fmac_f32_e32 v126, v180, v139
	v_fmac_f32_e32 v124, v181, v139
	ds_read_b128 v[144:147], v102 offset:46080
	ds_read_b128 v[152:155], v102 offset:46096
	v_fmac_f32_e32 v121, v177, v139
	v_pk_mul_f32 v[72:73], v[12:13], v[72:73]
	v_pk_mul_f32 v[66:67], v[66:67], v[90:91] op_sel_hi:[1,0]
	s_waitcnt lgkmcnt(9)
	v_fmac_f32_e32 v116, v182, v92
	v_fmac_f32_e32 v87, v183, v92
	v_fmac_f32_e32 v85, v184, v92
	v_fmac_f32_e32 v83, v185, v92
	s_waitcnt lgkmcnt(8)
	v_fmac_f32_e32 v120, v188, v92
	v_fmac_f32_e32 v119, v189, v92
	v_fmac_f32_e32 v118, v190, v92
	v_fmac_f32_e32 v117, v191, v92
	ds_read_b128 v[140:143], v102 offset:46112
	ds_read_b128 v[148:151], v102 offset:46128
	v_pk_mul_f32 v[68:69], v[68:69], v[90:91] op_sel_hi:[1,0]
	s_waitcnt lgkmcnt(9)
	v_fmac_f32_e32 v125, v192, v92
	v_fmac_f32_e32 v123, v193, v92
	v_fmac_f32_e32 v122, v194, v92
	v_fmac_f32_e32 v121, v195, v92
	s_waitcnt lgkmcnt(8)
	v_fmac_f32_e32 v128, v196, v92
	v_fmac_f32_e32 v127, v197, v92
	v_fmac_f32_e32 v126, v198, v92
	v_fmac_f32_e32 v124, v199, v92
	ds_read_b128 v[156:159], v103 offset:25600
	ds_read_b128 v[170:173], v103 offset:25616
	v_pk_mul_f32 v[68:69], v[16:17], v[68:69]
	s_waitcnt lgkmcnt(9)
	v_fmac_f32_e32 v116, v222, v93
	v_fmac_f32_e32 v87, v223, v93
	v_fmac_f32_e32 v85, v224, v93
	v_fmac_f32_e32 v83, v225, v93
	s_waitcnt lgkmcnt(8)
	v_fmac_f32_e32 v120, v226, v93
	v_fmac_f32_e32 v119, v227, v93
	v_fmac_f32_e32 v118, v228, v93
	v_fmac_f32_e32 v117, v229, v93
	ds_read_b128 v[178:181], v103 offset:25632
	ds_read_b128 v[174:177], v103 offset:25648
	s_waitcnt lgkmcnt(9)
	v_fmac_f32_e32 v125, v230, v93
	v_fmac_f32_e32 v123, v231, v93
	v_fmac_f32_e32 v122, v232, v93
	v_fmac_f32_e32 v121, v233, v93
	s_waitcnt lgkmcnt(8)
	v_fmac_f32_e32 v128, v234, v93
	v_fmac_f32_e32 v127, v235, v93
	v_fmac_f32_e32 v126, v236, v93
	v_fmac_f32_e32 v124, v237, v93
	v_lshlrev_b64 v[92:93], 11, v[88:89]
	v_lshl_add_u64 v[92:93], v[80:81], 0, v[92:93]
	global_store_dwordx2 v[92:93], v[94:95], off
	v_pk_mul_f32 v[94:95], v[6:7], v[74:75]
	s_nop 0
	v_cvt_pk_bf16_f32 v74, v94, v95
	v_cvt_pk_bf16_f32 v75, v76, v77
	ds_read_b128 v[182:185], v103 offset:46080
	ds_read_b128 v[188:191], v103 offset:46096
	s_waitcnt lgkmcnt(9)
	v_fmac_f32_e32 v116, v144, v94
	v_fmac_f32_e32 v87, v145, v94
	v_fmac_f32_e32 v85, v146, v94
	v_fmac_f32_e32 v83, v147, v94
	s_waitcnt lgkmcnt(8)
	v_fmac_f32_e32 v120, v152, v94
	v_fmac_f32_e32 v119, v153, v94
	v_fmac_f32_e32 v118, v154, v94
	v_fmac_f32_e32 v117, v155, v94
	ds_read_b128 v[192:195], v103 offset:46112
	ds_read_b128 v[196:199], v103 offset:46128
	s_waitcnt lgkmcnt(9)
	v_fmac_f32_e32 v125, v140, v94
	v_fmac_f32_e32 v123, v141, v94
	v_fmac_f32_e32 v122, v142, v94
	v_fmac_f32_e32 v121, v143, v94
	s_waitcnt lgkmcnt(8)
	v_fmac_f32_e32 v128, v148, v94
	v_fmac_f32_e32 v127, v149, v94
	v_fmac_f32_e32 v126, v150, v94
	v_fmac_f32_e32 v124, v151, v94
	ds_read_b128 v[222:225], v104
	ds_read_b128 v[226:229], v105
	s_waitcnt lgkmcnt(9)
	v_fmac_f32_e32 v116, v156, v95
	v_fmac_f32_e32 v87, v157, v95
	v_fmac_f32_e32 v85, v158, v95
	v_fmac_f32_e32 v83, v159, v95
	s_waitcnt lgkmcnt(8)
	v_fmac_f32_e32 v120, v170, v95
	v_fmac_f32_e32 v119, v171, v95
	v_fmac_f32_e32 v118, v172, v95
	v_fmac_f32_e32 v117, v173, v95
	ds_read_b128 v[230:233], v106
	ds_read_b128 v[234:237], v107
	s_waitcnt lgkmcnt(9)
	v_fmac_f32_e32 v125, v95, v178
	v_fmac_f32_e32 v123, v95, v179
	v_fmac_f32_e32 v122, v95, v180
	v_fmac_f32_e32 v121, v95, v181
	s_waitcnt lgkmcnt(8)
	v_fmac_f32_e32 v128, v95, v174
	v_fmac_f32_e32 v127, v95, v175
	v_fmac_f32_e32 v126, v95, v176
	v_fmac_f32_e32 v124, v95, v177
	ds_read_b128 v[144:147], v102 offset:51200
	ds_read_b128 v[152:155], v102 offset:51216
	v_pk_mul_f32 v[94:95], v[10:11], v[70:71]
	s_waitcnt lgkmcnt(9)
	v_fmac_f32_e32 v116, v76, v182
	v_fmac_f32_e32 v87, v76, v183
	v_fmac_f32_e32 v85, v76, v184
	v_fmac_f32_e32 v83, v76, v185
	s_waitcnt lgkmcnt(8)
	v_fmac_f32_e32 v120, v76, v188
	v_fmac_f32_e32 v119, v76, v189
	v_fmac_f32_e32 v118, v76, v190
	v_fmac_f32_e32 v117, v76, v191
	ds_read_b128 v[140:143], v102 offset:51232
	ds_read_b128 v[148:151], v102 offset:51248
	s_waitcnt lgkmcnt(9)
	v_fmac_f32_e32 v125, v76, v192
	v_fmac_f32_e32 v123, v76, v193
	v_fmac_f32_e32 v122, v76, v194
	v_fmac_f32_e32 v121, v76, v195
	s_waitcnt lgkmcnt(8)
; #define LAS __attribute__((address_space(3)))
; __device__ __forceinline__ unsigned cvt_pk_bf16(float lo, float hi) { unsigned r; asm volatile("v_cvt_pk_bf16_f32 %0, %1, %2" : "=v"(r) : "v"(lo), "v"(hi)); return r; }
; __device__ void phase0(const Params& P, LAS unsigned char* lds, const int G, const int bid) {
;     ...
;               for (int i = 0; i < 4; ++i) { v[i] = v[i] * rstd * w4[i];
;                   u32x2 w; w.x = cvt_pk_bf16(v[i][0], v[i][1]); w.y = cvt_pk_bf16(v[i][2], v[i][3]);
;                   *(u32x2*)(abf + (size_t)row * DM + 4 * lane + 256 * i) = w;
; #pragma unroll
;                   for (int j = 0; j < 4; ++j) { const LAS float* wr_ = wg + (j * 256 + i * 64 + lane) * 20; const float a = v[i][j];
; #pragma unroll
;                       for (int q = 0; q < 4; ++q) { const f32x4 wv = *(const LAS f32x4*)(wr_ + 4 * q);
;                           ga[4 * q] += a * wv[0]; ga[4 * q + 1] += a * wv[1]; ga[4 * q + 2] += a * wv[2]; ga[4 * q + 3] += a * wv[3]; } } }
	v_fmac_f32_e32 v128, v76, v196
	v_fmac_f32_e32 v127, v76, v197
	v_fmac_f32_e32 v126, v76, v198
	v_fmac_f32_e32 v124, v76, v199
	ds_read_b128 v[156:159], v103 offset:30720
	ds_read_b128 v[170:173], v103 offset:30736
	s_waitcnt lgkmcnt(9)
	v_fmac_f32_e32 v116, v77, v222
	v_fmac_f32_e32 v87, v77, v223
	v_fmac_f32_e32 v85, v77, v224
	v_fmac_f32_e32 v83, v77, v225
	s_waitcnt lgkmcnt(8)
	v_fmac_f32_e32 v120, v77, v226
	v_fmac_f32_e32 v119, v77, v227
	v_fmac_f32_e32 v118, v77, v228
	v_fmac_f32_e32 v117, v77, v229
	ds_read_b128 v[178:181], v103 offset:30752
	ds_read_b128 v[174:177], v103 offset:30768
	global_store_dwordx2 v[92:93], v[74:75], off offset:512
	v_cvt_pk_bf16_f32 v70, v94, v95
	v_cvt_pk_bf16_f32 v71, v72, v73
	s_waitcnt lgkmcnt(9)
	v_fmac_f32_e32 v125, v77, v230
	v_fmac_f32_e32 v123, v77, v231
	v_fmac_f32_e32 v122, v77, v232
	v_fmac_f32_e32 v121, v77, v233
	s_waitcnt lgkmcnt(8)
	v_fmac_f32_e32 v128, v77, v234
	v_fmac_f32_e32 v127, v77, v235
	v_fmac_f32_e32 v126, v77, v236
	v_fmac_f32_e32 v124, v77, v237
	ds_read_b128 v[182:185], v103 offset:51200
	ds_read_b128 v[188:191], v103 offset:51216
	s_waitcnt lgkmcnt(9)
	v_fmac_f32_e32 v116, v94, v144
	v_fmac_f32_e32 v87, v94, v145
	v_fmac_f32_e32 v85, v94, v146
	v_fmac_f32_e32 v83, v94, v147
	s_waitcnt lgkmcnt(8)
	v_fmac_f32_e32 v120, v94, v152
	v_fmac_f32_e32 v119, v94, v153
	v_fmac_f32_e32 v118, v94, v154
	v_fmac_f32_e32 v117, v94, v155
	ds_read_b128 v[192:195], v103 offset:51232
	ds_read_b128 v[196:199], v103 offset:51248
	s_waitcnt lgkmcnt(9)
	v_fmac_f32_e32 v125, v94, v140
	v_fmac_f32_e32 v123, v94, v141
	v_fmac_f32_e32 v122, v94, v142
	v_fmac_f32_e32 v121, v94, v143
	s_waitcnt lgkmcnt(8)
	v_fmac_f32_e32 v128, v94, v148
	v_fmac_f32_e32 v127, v94, v149
	v_fmac_f32_e32 v126, v94, v150
	v_fmac_f32_e32 v124, v94, v151
	ds_read_b128 v[222:225], v108
	ds_read_b128 v[226:229], v109
	s_waitcnt lgkmcnt(9)
	v_fmac_f32_e32 v116, v95, v156
	v_fmac_f32_e32 v87, v95, v157
	v_fmac_f32_e32 v85, v95, v158
	v_fmac_f32_e32 v83, v95, v159
	s_waitcnt lgkmcnt(8)
	v_fmac_f32_e32 v120, v95, v170
	v_fmac_f32_e32 v119, v95, v171
	v_fmac_f32_e32 v118, v95, v172
	v_fmac_f32_e32 v117, v95, v173
	ds_read_b128 v[230:233], v110
	ds_read_b128 v[234:237], v111
	s_waitcnt lgkmcnt(9)
	v_fmac_f32_e32 v125, v95, v178
	v_fmac_f32_e32 v123, v95, v179
	v_fmac_f32_e32 v122, v95, v180
	v_fmac_f32_e32 v121, v95, v181
	s_waitcnt lgkmcnt(8)
	v_fmac_f32_e32 v128, v95, v174
	v_fmac_f32_e32 v127, v95, v175
	v_fmac_f32_e32 v126, v95, v176
	v_fmac_f32_e32 v124, v95, v177
	ds_read_b128 v[144:147], v102 offset:56320
	ds_read_b128 v[152:155], v102 offset:56336
	v_pk_mul_f32 v[94:95], v[14:15], v[66:67]
	s_waitcnt lgkmcnt(9)
	v_fmac_f32_e32 v116, v72, v182
	v_fmac_f32_e32 v87, v72, v183
	v_fmac_f32_e32 v85, v72, v184
	v_fmac_f32_e32 v83, v72, v185
	s_waitcnt lgkmcnt(8)
	v_fmac_f32_e32 v120, v72, v188
	v_fmac_f32_e32 v119, v72, v189
	v_fmac_f32_e32 v118, v72, v190
	v_fmac_f32_e32 v117, v72, v191
	ds_read_b128 v[140:143], v102 offset:56352
	ds_read_b128 v[148:151], v102 offset:56368
	s_waitcnt lgkmcnt(9)
	v_fmac_f32_e32 v125, v72, v192
	v_fmac_f32_e32 v123, v72, v193
	v_fmac_f32_e32 v122, v72, v194
	v_fmac_f32_e32 v121, v72, v195
	s_waitcnt lgkmcnt(8)
	v_fmac_f32_e32 v128, v72, v196
	v_fmac_f32_e32 v127, v72, v197
	v_fmac_f32_e32 v126, v72, v198
	v_fmac_f32_e32 v124, v72, v199
	ds_read_b128 v[156:159], v103 offset:35840
	ds_read_b128 v[170:173], v103 offset:35856
	s_waitcnt lgkmcnt(9)
	v_fmac_f32_e32 v116, v73, v222
	v_fmac_f32_e32 v87, v73, v223
	v_fmac_f32_e32 v85, v73, v224
	v_fmac_f32_e32 v83, v73, v225
	s_waitcnt lgkmcnt(8)
	v_fmac_f32_e32 v120, v73, v226
	v_fmac_f32_e32 v119, v73, v227
	v_fmac_f32_e32 v118, v73, v228
	v_fmac_f32_e32 v117, v73, v229
	ds_read_b128 v[178:181], v103 offset:35872
	ds_read_b128 v[174:177], v103 offset:35888
	global_store_dwordx2 v[92:93], v[70:71], off offset:1024
	v_cvt_pk_bf16_f32 v66, v94, v95
	v_cvt_pk_bf16_f32 v67, v68, v69
	s_waitcnt lgkmcnt(9)
	v_fmac_f32_e32 v125, v73, v230
	v_fmac_f32_e32 v123, v73, v231
	v_fmac_f32_e32 v122, v73, v232
	v_fmac_f32_e32 v121, v73, v233
	s_waitcnt lgkmcnt(8)
	v_fmac_f32_e32 v128, v73, v234
	v_fmac_f32_e32 v127, v73, v235
	v_fmac_f32_e32 v126, v73, v236
	v_fmac_f32_e32 v124, v73, v237
	ds_read_b128 v[182:185], v103 offset:56320
	ds_read_b128 v[188:191], v103 offset:56336
	s_waitcnt lgkmcnt(9)
	v_fmac_f32_e32 v116, v94, v144
	v_fmac_f32_e32 v87, v94, v145
	v_fmac_f32_e32 v85, v94, v146
	v_fmac_f32_e32 v83, v94, v147
	s_waitcnt lgkmcnt(8)
	v_fmac_f32_e32 v120, v94, v152
	v_fmac_f32_e32 v119, v94, v153
	v_fmac_f32_e32 v118, v94, v154
	v_fmac_f32_e32 v117, v94, v155
	ds_read_b128 v[192:195], v103 offset:56352
	ds_read_b128 v[196:199], v103 offset:56368
	s_waitcnt lgkmcnt(9)
	v_fmac_f32_e32 v125, v94, v140
	v_fmac_f32_e32 v123, v94, v141
	v_fmac_f32_e32 v122, v94, v142
	v_fmac_f32_e32 v121, v94, v143
	s_waitcnt lgkmcnt(8)
	v_fmac_f32_e32 v128, v94, v148
	v_fmac_f32_e32 v127, v94, v149
	v_fmac_f32_e32 v126, v94, v150
	v_fmac_f32_e32 v124, v94, v151
	ds_read_b128 v[222:225], v112
	ds_read_b128 v[226:229], v113
	s_waitcnt lgkmcnt(9)
	v_fmac_f32_e32 v116, v95, v156
	v_fmac_f32_e32 v87, v95, v157
	v_fmac_f32_e32 v85, v95, v158
	v_fmac_f32_e32 v83, v95, v159
	s_waitcnt lgkmcnt(8)
	v_fmac_f32_e32 v120, v95, v170
	v_fmac_f32_e32 v119, v95, v171
	v_fmac_f32_e32 v118, v95, v172
	v_fmac_f32_e32 v117, v95, v173
	ds_read_b128 v[230:233], v114
	ds_read_b128 v[234:237], v115
	s_waitcnt lgkmcnt(9)
	v_fmac_f32_e32 v125, v95, v178
	v_fmac_f32_e32 v123, v95, v179
	v_fmac_f32_e32 v122, v95, v180
	v_fmac_f32_e32 v121, v95, v181
	s_waitcnt lgkmcnt(8)
; #define LAS __attribute__((address_space(3)))
; __device__ __forceinline__ float logsigmoidf_(float x) { return fminf(x, 0.0f) - log1pf(__expf(-fabsf(x))); }
; __device__ void phase0(const Params& P, LAS unsigned char* lds, const int G, const int bid) {
;     ...
;                   for (int j = 0; j < 4; ++j) { const LAS float* wr_ = wg + (j * 256 + i * 64 + lane) * 20; const float a = v[i][j];
; #pragma unroll
;                       for (int q = 0; q < 4; ++q) { const f32x4 wv = *(const LAS f32x4*)(wr_ + 4 * q);
;                           ga[4 * q] += a * wv[0]; ga[4 * q + 1] += a * wv[1]; ga[4 * q + 2] += a * wv[2]; ga[4 * q + 3] += a * wv[3]; } } }
;               float r8[8], r4[4], r2[2], r1;
; #pragma unroll
;               for (int c = 0; c < 8; ++c) { const bool hi = (lane & 32) != 0; const float send = hi ? ga[c] : ga[c + 8], keep = hi ? ga[c + 8] : ga[c]; r8[c] = keep + __shfl_xor(send, 32); }
; #pragma unroll
;               for (int c = 0; c < 4; ++c) { const bool hi = (lane & 16) != 0; const float send = hi ? r8[c] : r8[c + 4], keep = hi ? r8[c + 4] : r8[c]; r4[c] = keep + __shfl_xor(send, 16); }
; #pragma unroll
;               for (int c = 0; c < 2; ++c) { const bool hi = (lane & 8) != 0; const float send = hi ? r4[c] : r4[c + 2], keep = hi ? r4[c + 2] : r4[c]; r2[c] = keep + __shfl_xor(send, 8); }
;               { const bool hi = (lane & 4) != 0; const float send = hi ? r2[0] : r2[1], keep = hi ? r2[1] : r2[0]; r1 = keep + __shfl_xor(send, 4); }
;               r1 += __shfl_xor(r1, 2); r1 += __shfl_xor(r1, 1);
;               if ((lane & 3) == 0) { float gv = r1 + gbias; if (gcol >= 8) gv = logsigmoidf_(gv); gates[(size_t)row * 16 + gcol] = gv; }
	v_fmac_f32_e32 v128, v95, v174
	v_fmac_f32_e32 v127, v95, v175
	v_fmac_f32_e32 v126, v95, v176
	v_fmac_f32_e32 v124, v95, v177
	s_waitcnt lgkmcnt(7)
	v_fmac_f32_e32 v116, v68, v182
	v_fmac_f32_e32 v87, v68, v183
	v_fmac_f32_e32 v85, v68, v184
	v_fmac_f32_e32 v83, v68, v185
	s_waitcnt lgkmcnt(6)
	v_fmac_f32_e32 v120, v68, v188
	v_fmac_f32_e32 v119, v68, v189
	v_fmac_f32_e32 v118, v68, v190
	v_fmac_f32_e32 v117, v68, v191
	s_waitcnt lgkmcnt(5)
	v_fmac_f32_e32 v125, v68, v192
	v_fmac_f32_e32 v123, v68, v193
	v_fmac_f32_e32 v122, v68, v194
	v_fmac_f32_e32 v121, v68, v195
	s_waitcnt lgkmcnt(4)
	v_fmac_f32_e32 v128, v68, v196
	v_fmac_f32_e32 v127, v68, v197
	v_fmac_f32_e32 v126, v68, v198
	v_fmac_f32_e32 v124, v68, v199
	s_waitcnt lgkmcnt(3)
	v_fmac_f32_e32 v116, v69, v222
	v_fmac_f32_e32 v87, v69, v223
	v_fmac_f32_e32 v85, v69, v224
	v_fmac_f32_e32 v83, v69, v225
	s_waitcnt lgkmcnt(2)
	v_fmac_f32_e32 v120, v69, v226
	v_fmac_f32_e32 v119, v69, v227
	v_fmac_f32_e32 v118, v69, v228
	v_fmac_f32_e32 v117, v69, v229
	global_store_dwordx2 v[92:93], v[66:67], off offset:1536
	s_waitcnt lgkmcnt(1)
	v_fmac_f32_e32 v125, v69, v230
	v_fmac_f32_e32 v123, v69, v231
	v_fmac_f32_e32 v122, v69, v232
	v_fmac_f32_e32 v121, v69, v233
	s_waitcnt lgkmcnt(0)
	v_fmac_f32_e32 v128, v69, v234
	v_fmac_f32_e32 v127, v69, v235
	v_fmac_f32_e32 v126, v69, v236
	v_fmac_f32_e32 v124, v69, v237
	v_cndmask_b32_e32 v140, v116, v125, vcc
	v_cndmask_b32_e32 v141, v87, v123, vcc
	v_cndmask_b32_e32 v142, v85, v122, vcc
	v_cndmask_b32_e32 v143, v125, v116, vcc
	v_cndmask_b32_e32 v144, v123, v87, vcc
	v_cndmask_b32_e32 v145, v122, v85, vcc
	v_cndmask_b32_e32 v146, v83, v121, vcc
	v_cndmask_b32_e32 v147, v120, v128, vcc
	v_cndmask_b32_e32 v148, v119, v127, vcc
	v_cndmask_b32_e32 v149, v121, v83, vcc
	v_cndmask_b32_e32 v150, v128, v120, vcc
	v_cndmask_b32_e32 v151, v127, v119, vcc
	v_cndmask_b32_e32 v152, v118, v126, vcc
	v_cndmask_b32_e32 v153, v117, v124, vcc
	v_cndmask_b32_e32 v154, v126, v118, vcc
	v_cndmask_b32_e32 v155, v124, v117, vcc
	ds_bpermute_b32 v156, v96, v140
	ds_bpermute_b32 v157, v96, v141
	ds_bpermute_b32 v158, v96, v142
	ds_bpermute_b32 v159, v96, v146
	ds_bpermute_b32 v170, v96, v147
	ds_bpermute_b32 v171, v96, v148
	ds_bpermute_b32 v172, v96, v152
	ds_bpermute_b32 v173, v96, v153
	s_waitcnt lgkmcnt(7)
	v_add_f32_e32 v174, v143, v156
	s_waitcnt lgkmcnt(6)
	v_add_f32_e32 v175, v144, v157
	s_waitcnt lgkmcnt(5)
	v_add_f32_e32 v176, v145, v158
	s_waitcnt lgkmcnt(4)
	v_add_f32_e32 v177, v149, v159
	s_waitcnt lgkmcnt(3)
	v_add_f32_e32 v178, v150, v170
	s_waitcnt lgkmcnt(2)
	v_add_f32_e32 v179, v151, v171
	s_waitcnt lgkmcnt(1)
	v_add_f32_e32 v74, v154, v172
	s_waitcnt lgkmcnt(0)
	v_add_f32_e32 v75, v155, v173
	v_cndmask_b32_e64 v180, v174, v178, s[42:43]
	v_cndmask_b32_e64 v181, v178, v174, s[42:43]
	v_cndmask_b32_e64 v182, v175, v179, s[42:43]
	v_cndmask_b32_e64 v183, v179, v175, s[42:43]
	v_cndmask_b32_e64 v184, v176, v74, s[42:43]
	v_cndmask_b32_e64 v185, v177, v75, s[42:43]
	v_cndmask_b32_e64 v188, v74, v176, s[42:43]
	v_cndmask_b32_e64 v189, v75, v177, s[42:43]
	ds_bpermute_b32 v77, v97, v180
	ds_bpermute_b32 v190, v97, v182
	ds_bpermute_b32 v191, v97, v184
	ds_bpermute_b32 v76, v97, v185
	s_waitcnt lgkmcnt(3)
	v_add_f32_e32 v192, v181, v77
	s_waitcnt lgkmcnt(2)
	v_add_f32_e32 v193, v183, v190
	s_waitcnt lgkmcnt(1)
	v_add_f32_e32 v194, v188, v191
	s_waitcnt lgkmcnt(0)
	v_add_f32_e32 v71, v189, v76
	v_cndmask_b32_e64 v195, v192, v194, s[44:45]
	v_cndmask_b32_e64 v196, v193, v71, s[44:45]
	v_cndmask_b32_e64 v197, v194, v192, s[44:45]
	v_cndmask_b32_e64 v198, v71, v193, s[44:45]
	ds_bpermute_b32 v72, v98, v195
	ds_bpermute_b32 v73, v98, v196
	s_waitcnt lgkmcnt(1)
	v_add_f32_e32 v199, v197, v72
	s_waitcnt lgkmcnt(0)
	v_add_f32_e32 v222, v198, v73
	v_cndmask_b32_e64 v223, v199, v222, s[46:47]
	v_cndmask_b32_e64 v224, v222, v199, s[46:47]
	ds_bpermute_b32 v70, v99, v223
	s_waitcnt lgkmcnt(0)
	v_add_f32_e32 v225, v224, v70
	ds_bpermute_b32 v226, v100, v225
	s_waitcnt lgkmcnt(0)
	v_add_f32_e32 v68, v225, v226
	ds_bpermute_b32 v69, v101, v68
	s_and_saveexec_b64 s[6:7], s[48:49]
	s_cbranch_execz .LBB0_1050
	s_waitcnt lgkmcnt(0)
	v_add_f32_e32 v66, v68, v69
	v_add_f32_e32 v66, v91, v66
	s_and_saveexec_b64 s[8:9], s[40:41]
	s_cbranch_execz .LBB0_1049
; __device__ __forceinline__ float logsigmoidf_(float x) { return fminf(x, 0.0f) - log1pf(__expf(-fabsf(x))); }
; __device__ void phase0(const Params& P, LAS unsigned char* lds, const int G, const int bid) {
;     ...
;               if ((lane & 3) == 0) { float gv = r1 + gbias; if (gcol >= 8) gv = logsigmoidf_(gv); gates[(size_t)row * 16 + gcol] = gv; }
	s_mov_b32 s12, 0xbfb8aa3b
	v_mul_f32_e64 v67, |v66|, s12
	v_exp_f32_e32 v83, v67
	v_max_f32_e32 v66, v66, v66
	v_min_f32_e32 v85, 0, v66
	s_mov_b32 s12, 0x3f2aaaab
	v_add_f32_e32 v68, 1.0, v83
	v_add_f32_e32 v66, -1.0, v68
	v_sub_f32_e32 v67, v66, v68
	v_sub_f32_e32 v66, v83, v66
	v_add_f32_e32 v67, 1.0, v67
	v_add_f32_e32 v69, v66, v67
	v_frexp_mant_f32_e32 v70, v68
	v_cvt_f64_f32_e32 v[66:67], v68
	v_frexp_exp_i32_f64_e32 v66, v[66:67]
	v_cmp_gt_f32_e64 s[50:51], s12, v70
	s_mov_b32 s12, 0x3f317218
	s_nop 0
	v_subbrev_co_u32_e64 v74, s[50:51], 0, v66, s[50:51]
	v_sub_u32_e32 v66, 0, v74
	v_ldexp_f32 v67, v68, v66
	v_add_f32_e32 v68, -1.0, v67
	v_add_f32_e32 v70, 1.0, v67
	v_ldexp_f32 v66, v69, v66
	v_add_f32_e32 v69, 1.0, v68
	v_add_f32_e32 v71, -1.0, v70
	v_sub_f32_e32 v69, v67, v69
	v_sub_f32_e32 v67, v67, v71
	v_add_f32_e32 v69, v66, v69
	v_add_f32_e32 v66, v66, v67
	v_add_f32_e32 v75, v70, v66
	v_rcp_f32_e32 v77, v75
	v_sub_f32_e32 v67, v75, v70
	v_sub_f32_e32 v76, v66, v67
	v_add_f32_e32 v67, v68, v69
	v_mul_f32_e32 v90, v67, v77
	v_sub_f32_e32 v66, v67, v68
	v_mul_f32_e32 v68, v75, v90
	v_fma_f32 v70, v90, v75, -v68
	v_fmac_f32_e32 v70, v90, v76
	v_sub_f32_e32 v87, v69, v66
	v_add_f32_e32 v66, v68, v70
	v_sub_f32_e32 v69, v67, v66
	v_pk_add_f32 v[72:73], v[66:67], v[68:69] neg_lo:[0,1] neg_hi:[0,1]
	v_mov_b32_e32 v71, v66
	v_pk_add_f32 v[66:67], v[72:73], v[70:71] neg_lo:[0,1] neg_hi:[0,1]
	s_nop 0
	v_add_f32_e32 v67, v87, v67
	v_add_f32_e32 v66, v66, v67
	v_add_f32_e32 v67, v69, v66
	v_mul_f32_e32 v87, v77, v67
	v_mul_f32_e32 v68, v75, v87
	v_fma_f32 v70, v87, v75, -v68
	v_fmac_f32_e32 v70, v87, v76
	v_sub_f32_e32 v69, v69, v67
	v_add_f32_e32 v75, v66, v69
	v_add_f32_e32 v66, v68, v70
	v_sub_f32_e32 v69, v67, v66
	v_pk_add_f32 v[72:73], v[66:67], v[68:69] neg_lo:[0,1] neg_hi:[0,1]
	v_mov_b32_e32 v71, v66
	v_pk_add_f32 v[66:67], v[72:73], v[70:71] neg_lo:[0,1] neg_hi:[0,1]
	s_nop 0
	v_add_f32_e32 v67, v75, v67
	v_add_f32_e32 v66, v66, v67
	v_add_f32_e32 v67, v90, v87
	v_add_f32_e32 v66, v69, v66
	v_sub_f32_e32 v68, v67, v90
	v_mul_f32_e32 v66, v77, v66
	v_sub_f32_e32 v68, v87, v68
	v_add_f32_e32 v68, v68, v66
	v_add_f32_e32 v70, v67, v68
	v_mul_f32_e32 v71, v70, v70
	v_fmamk_f32 v66, v71, 0x3e9b6dac, v208
	v_fmaak_f32 v169, v71, v66, 0x3f2aaada
	v_cvt_f32_i32_e32 v66, v74
	v_sub_f32_e32 v67, v70, v67
	v_sub_f32_e32 v67, v68, v67
	v_ldexp_f32 v72, v67, 1
	v_mul_f32_e32 v67, v70, v71
	v_ldexp_f32 v69, v70, 1
	v_pk_mul_f32 v[70:71], v[66:67], v[168:169]
	s_nop 0
	v_fma_f32 v68, v66, s12, -v70
	v_fmac_f32_e32 v68, 0xb102e308, v66
	v_pk_add_f32 v[66:67], v[70:71], v[68:69]
	s_mov_b32 s12, 0x7f800000
	v_sub_f32_e32 v69, v67, v69
	v_sub_f32_e32 v69, v71, v69
	v_add_f32_e32 v73, v72, v69
	v_mov_b32_e32 v72, v70
	v_pk_add_f32 v[70:71], v[66:67], v[70:71] neg_lo:[0,1] neg_hi:[0,1]
	v_pk_add_f32 v[74:75], v[66:67], v[72:73]
	v_mov_b32_e32 v69, v66
	v_mov_b32_e32 v71, v75
	v_pk_add_f32 v[76:77], v[68:69], v[70:71] neg_lo:[0,1] neg_hi:[0,1]
	v_pk_add_f32 v[68:69], v[68:69], v[70:71]
	v_mov_b32_e32 v72, v73
	v_pk_add_f32 v[70:71], v[68:69], v[66:67] op_sel:[1,0] op_sel_hi:[0,1] neg_lo:[0,1] neg_hi:[0,1]
	s_nop 0
	v_pk_add_f32 v[92:93], v[74:75], v[70:71] op_sel_hi:[1,0] neg_lo:[0,1] neg_hi:[0,1]
	v_mov_b32_e32 v74, v75
	v_mov_b32_e32 v75, v69
	v_pk_mov_b32 v[70:71], v[66:67], v[70:71] op_sel:[1,0]
	v_mov_b32_e32 v73, v66
	v_pk_add_f32 v[70:71], v[74:75], v[70:71] neg_lo:[0,1] neg_hi:[0,1]
	v_mov_b32_e32 v92, v76
	v_pk_add_f32 v[66:67], v[72:73], v[70:71] neg_lo:[0,1] neg_hi:[0,1]
	v_mov_b32_e32 v77, v69
	v_pk_add_f32 v[70:71], v[92:93], v[66:67]
	v_cmp_neq_f32_e64 s[50:51], s12, v83
	v_pk_add_f32 v[72:73], v[70:71], v[70:71] op_sel:[0,1] op_sel_hi:[1,0]
	s_mov_b32 s12, 0x33800000
	v_pk_add_f32 v[68:69], v[68:69], v[72:73] op_sel:[1,0] op_sel_hi:[0,1]
	s_nop 0
	v_mov_b32_e32 v71, v68
	v_pk_add_f32 v[74:75], v[70:71], v[76:77] neg_lo:[0,1] neg_hi:[0,1]
	v_mov_b32_e32 v67, v72
	v_sub_f32_e32 v69, v70, v74
	v_pk_add_f32 v[66:67], v[66:67], v[74:75] neg_lo:[0,1] neg_hi:[0,1]
	v_sub_f32_e32 v69, v76, v69
	v_add_f32_e32 v66, v66, v69
	v_add_f32_e32 v66, v66, v67
	v_add_f32_e32 v66, v68, v66
	v_cndmask_b32_e64 v66, v212, v66, s[50:51]
	v_cmp_ngt_f32_e64 s[50:51], -1.0, v83
	s_nop 1
	v_cndmask_b32_e64 v66, v213, v66, s[50:51]
	v_cmp_neq_f32_e64 s[50:51], -1.0, v83
	s_nop 1
	v_cndmask_b32_e64 v66, v214, v66, s[50:51]
	v_cmp_lt_f32_e64 s[50:51], |v83|, s12
	s_nop 1
	v_cndmask_b32_e64 v66, v66, v83, s[50:51]
	v_sub_f32_e32 v66, v85, v66

; #define LAS __attribute__((address_space(3)))
; __device__ __forceinline__ unsigned cvt_pk_bf16(float lo, float hi) { unsigned r; asm volatile("v_cvt_pk_bf16_f32 %0, %1, %2" : "=v"(r) : "v"(lo), "v"(hi)); return r; }
; __device__ void phase0(const Params& P, LAS unsigned char* lds, const int G, const int bid) {
;     ...
;           for (int rr = 0; rr < 4; ++rr) { const int row = row0 + rr * G * 8; if (row >= NTOK) continue;
;               f32x4 (&v)[4] = vv[rr]; float ss = 0.f;
; #pragma unroll
;               for (int i = 0; i < 4; ++i)
; #pragma unroll
;                   for (int j = 0; j < 4; ++j) ss += v[i][j] * v[i][j];
; #pragma unroll
;               for (int o = 32; o >= 1; o >>= 1) ss += __shfl_xor(ss, o);
;               const float rstd = rsqrtf(ss * (1.0f / DM) + 1e-6f);
;               float ga[16];
; #pragma unroll
;               for (int c = 0; c < 16; ++c) ga[c] = 0.f;
; #pragma unroll
;               for (int i = 0; i < 4; ++i) { v[i] = v[i] * rstd * w4[i];
;                   u32x2 w; w.x = cvt_pk_bf16(v[i][0], v[i][1]); w.y = cvt_pk_bf16(v[i][2], v[i][3]);
;                   *(u32x2*)(abf + (size_t)row * DM + 4 * lane + 256 * i) = w;
; #pragma unroll
;                   for (int j = 0; j < 4; ++j) { const LAS float* wr_ = wg + (j * 256 + i * 64 + lane) * 20; const float a = v[i][j];
; #pragma unroll
;                       for (int q = 0; q < 4; ++q) { const f32x4 wv = *(const LAS f32x4*)(wr_ + 4 * q);
;                           ga[4 * q] += a * wv[0]; ga[4 * q + 1] += a * wv[1]; ga[4 * q + 2] += a * wv[2]; ga[4 * q + 3] += a * wv[3]; } } }
.LBB0_1050:
	s_or_b64 exec, exec, s[6:7]
	v_cmp_gt_i32_e64 s[50:51], s15, v82
	s_and_saveexec_b64 s[6:7], s[50:51]
	s_cbranch_execz .LBB0_1055
	s_waitcnt vmcnt(15)
	v_mul_f32_e32 v70, v63, v63
	v_fmac_f32_e32 v70, v62, v62
	v_fmac_f32_e32 v70, v64, v64
	v_fmac_f32_e32 v70, v65, v65
	s_waitcnt vmcnt(14)
	v_fmac_f32_e32 v70, v58, v58
	v_fmac_f32_e32 v70, v59, v59
	v_fmac_f32_e32 v70, v60, v60
	v_fmac_f32_e32 v70, v61, v61
	s_waitcnt vmcnt(13)
	v_fmac_f32_e32 v70, v54, v54
	v_fmac_f32_e32 v70, v55, v55
	v_fmac_f32_e32 v70, v56, v56
	v_fmac_f32_e32 v70, v57, v57
	s_waitcnt vmcnt(12) lgkmcnt(0)
	v_pk_mul_f32 v[68:69], v[50:51], v[50:51]
	v_pk_mul_f32 v[66:67], v[52:53], v[52:53]
	v_add_f32_e32 v68, v68, v70
	v_add_f32_e32 v68, v69, v68
	v_add_f32_e32 v66, v66, v68
	v_add_f32_e32 v66, v67, v66
	ds_bpermute_b32 v67, v96, v66
	v_ashrrev_i32_e32 v83, 31, v82
	v_lshlrev_b64 v[68:69], 11, v[82:83]
	v_lshl_add_u64 v[68:69], v[80:81], 0, v[68:69]
	s_waitcnt lgkmcnt(0)
	v_add_f32_e32 v66, v66, v67
	ds_bpermute_b32 v67, v97, v66
	s_waitcnt lgkmcnt(0)
	v_add_f32_e32 v66, v66, v67
	ds_bpermute_b32 v67, v98, v66
	s_waitcnt lgkmcnt(0)
	v_add_f32_e32 v66, v66, v67
	ds_bpermute_b32 v67, v99, v66
	s_waitcnt lgkmcnt(0)
	v_add_f32_e32 v66, v66, v67
	ds_bpermute_b32 v67, v100, v66
	s_waitcnt lgkmcnt(0)
	v_add_f32_e32 v66, v66, v67
	ds_bpermute_b32 v67, v101, v66
	s_waitcnt lgkmcnt(0)
	v_add_f32_e32 v66, v66, v67
	v_fmamk_f32 v66, v66, 0x3a800000, v210
	v_cmp_gt_f32_e64 s[50:51], s30, v66
	v_mul_f32_e32 v67, 0x4b800000, v66
	s_nop 0
	v_cndmask_b32_e64 v66, v66, v67, s[50:51]
	v_rsq_f32_e32 v66, v66
	s_nop 0
	v_mul_f32_e32 v67, 0x45800000, v66
	v_cndmask_b32_e64 v66, v66, v67, s[50:51]
	v_pk_mul_f32 v[70:71], v[62:63], v[66:67] op_sel_hi:[1,0]
	v_pk_mul_f32 v[62:63], v[64:65], v[66:67] op_sel_hi:[1,0]
	v_pk_mul_f32 v[64:65], v[2:3], v[70:71]
	v_pk_mul_f32 v[62:63], v[4:5], v[62:63]
	v_cvt_pk_bf16_f32 v70, v64, v65
	s_nop 0
	v_cvt_pk_bf16_f32 v71, v62, v63
	global_store_dwordx2 v[68:69], v[70:71], off
	ds_read_b128 v[140:143], v102 offset:40960
	ds_read_b128 v[144:147], v102 offset:40976
	ds_read_b128 v[148:151], v102 offset:40992
	ds_read_b128 v[152:155], v102 offset:41008
	ds_read_b128 v[156:159], v102 offset:61440
	ds_read_b128 v[170:173], v102 offset:61456
	ds_read_b128 v[174:177], v102 offset:61472
	ds_read_b128 v[178:181], v102 offset:61488
	ds_read_b128 v[182:185], v103 offset:40960
	ds_read_b128 v[188:191], v103 offset:40976
	ds_read_b128 v[192:195], v103 offset:40992
	ds_read_b128 v[196:199], v103 offset:41008
	s_waitcnt lgkmcnt(11)
	v_fma_f32 v89, v140, v64, 0
	s_waitcnt lgkmcnt(10)
	v_fma_f32 v74, v144, v64, 0
	s_waitcnt lgkmcnt(9)
	v_fma_f32 v92, v148, v64, 0
	v_fma_f32 v90, v149, v64, 0
	v_fma_f32 v87, v150, v64, 0
	v_fma_f32 v77, v151, v64, 0
	ds_read_b128 v[222:225], v103 offset:61440
	v_fma_f32 v88, v141, v64, 0
	v_fma_f32 v85, v142, v64, 0
	v_fma_f32 v75, v143, v64, 0
	v_fma_f32 v72, v145, v64, 0
	s_waitcnt lgkmcnt(8)
	v_fmac_f32_e32 v89, v156, v65
	v_fmac_f32_e32 v88, v157, v65
	v_fmac_f32_e32 v85, v158, v65
	v_fmac_f32_e32 v75, v159, v65
	ds_read_b128 v[226:229], v103 offset:61456
	v_fma_f32 v70, v146, v64, 0
	v_fma_f32 v67, v147, v64, 0
	v_fma_f32 v76, v152, v64, 0
	v_fma_f32 v73, v153, v64, 0
	s_waitcnt lgkmcnt(8)
	v_fmac_f32_e32 v74, v170, v65
	v_fmac_f32_e32 v72, v171, v65
	v_fmac_f32_e32 v70, v172, v65
	v_fmac_f32_e32 v67, v173, v65
	ds_read_b128 v[230:233], v103 offset:61472
	v_fma_f32 v71, v154, v64, 0
	v_fma_f32 v64, v155, v64, 0
	s_waitcnt lgkmcnt(8)
	v_fmac_f32_e32 v92, v174, v65
	v_fmac_f32_e32 v90, v175, v65
	v_fmac_f32_e32 v87, v176, v65
	v_fmac_f32_e32 v77, v177, v65
	ds_read_b128 v[234:237], v103 offset:61488
	s_waitcnt lgkmcnt(8)
	v_fmac_f32_e32 v76, v178, v65
	v_fmac_f32_e32 v73, v179, v65
	v_fmac_f32_e32 v71, v180, v65
	v_fmac_f32_e32 v64, v181, v65
	ds_read_b128 v[148:151], v102 offset:46080
	ds_read_b128 v[140:143], v102 offset:46096
	ds_read_b128 v[156:159], v102 offset:46112
	ds_read_b128 v[144:147], v102 offset:46128
	s_waitcnt lgkmcnt(11)
	v_fmac_f32_e32 v89, v182, v62
	v_fmac_f32_e32 v88, v183, v62
	v_fmac_f32_e32 v85, v184, v62
	v_fmac_f32_e32 v75, v185, v62
	ds_read_b128 v[170:173], v103 offset:25600
	s_waitcnt lgkmcnt(11)
	v_fmac_f32_e32 v74, v62, v188
	v_fmac_f32_e32 v72, v62, v189
	v_fmac_f32_e32 v70, v62, v190
	v_fmac_f32_e32 v67, v62, v191
	s_waitcnt lgkmcnt(8)
	v_fmac_f32_e32 v89, v63, v222
	v_fmac_f32_e32 v88, v63, v223
	v_fmac_f32_e32 v85, v63, v224
	v_fmac_f32_e32 v75, v63, v225
	ds_read_b128 v[152:155], v103 offset:25616
	v_fmac_f32_e32 v92, v62, v192
	v_fmac_f32_e32 v90, v62, v193
	v_fmac_f32_e32 v87, v62, v194
	v_fmac_f32_e32 v77, v62, v195
	s_waitcnt lgkmcnt(8)
	v_fmac_f32_e32 v74, v63, v226
	v_fmac_f32_e32 v72, v63, v227
	v_fmac_f32_e32 v70, v63, v228
	v_fmac_f32_e32 v67, v63, v229
	ds_read_b128 v[174:177], v103 offset:25632
	v_fmac_f32_e32 v76, v62, v196
	v_fmac_f32_e32 v73, v62, v197
	v_fmac_f32_e32 v71, v62, v198
	v_fmac_f32_e32 v64, v62, v199
	s_waitcnt lgkmcnt(8)
	v_fmac_f32_e32 v92, v63, v230
	v_fmac_f32_e32 v90, v63, v231
	v_fmac_f32_e32 v87, v63, v232
	v_fmac_f32_e32 v77, v63, v233
	ds_read_b128 v[178:181], v103 offset:25648
	s_waitcnt lgkmcnt(8)
	v_fmac_f32_e32 v76, v63, v234
	v_fmac_f32_e32 v73, v63, v235
	v_fmac_f32_e32 v71, v63, v236
	v_fmac_f32_e32 v64, v63, v237
	v_pk_mul_f32 v[62:63], v[58:59], v[66:67] op_sel_hi:[1,0]
	v_pk_mul_f32 v[58:59], v[60:61], v[66:67] op_sel_hi:[1,0]
	v_pk_mul_f32 v[94:95], v[6:7], v[62:63]
	v_pk_mul_f32 v[58:59], v[8:9], v[58:59]
	v_cvt_pk_bf16_f32 v60, v94, v95
	s_nop 0
	v_cvt_pk_bf16_f32 v61, v58, v59
	global_store_dwordx2 v[68:69], v[60:61], off offset:512
	ds_read_b128 v[182:185], v103 offset:46080
	ds_read_b128 v[188:191], v103 offset:46096
	ds_read_b128 v[222:225], v103 offset:46112
	ds_read_b128 v[192:195], v103 offset:46128
	s_waitcnt lgkmcnt(11)
; #define LAS __attribute__((address_space(3)))
; __device__ __forceinline__ unsigned cvt_pk_bf16(float lo, float hi) { unsigned r; asm volatile("v_cvt_pk_bf16_f32 %0, %1, %2" : "=v"(r) : "v"(lo), "v"(hi)); return r; }
; __device__ void phase0(const Params& P, LAS unsigned char* lds, const int G, const int bid) {
;     ...
;               for (int i = 0; i < 4; ++i) { v[i] = v[i] * rstd * w4[i];
;                   u32x2 w; w.x = cvt_pk_bf16(v[i][0], v[i][1]); w.y = cvt_pk_bf16(v[i][2], v[i][3]);
;                   *(u32x2*)(abf + (size_t)row * DM + 4 * lane + 256 * i) = w;
; #pragma unroll
;                   for (int j = 0; j < 4; ++j) { const LAS float* wr_ = wg + (j * 256 + i * 64 + lane) * 20; const float a = v[i][j];
; #pragma unroll
;                       for (int q = 0; q < 4; ++q) { const f32x4 wv = *(const LAS f32x4*)(wr_ + 4 * q);
;                           ga[4 * q] += a * wv[0]; ga[4 * q + 1] += a * wv[1]; ga[4 * q + 2] += a * wv[2]; ga[4 * q + 3] += a * wv[3]; } } }
	v_fmac_f32_e32 v89, v94, v148
	v_fmac_f32_e32 v88, v94, v149
	v_fmac_f32_e32 v85, v94, v150
	v_fmac_f32_e32 v75, v94, v151
	s_waitcnt lgkmcnt(10)
	v_fmac_f32_e32 v74, v94, v140
	v_fmac_f32_e32 v72, v94, v141
	v_fmac_f32_e32 v70, v94, v142
	v_fmac_f32_e32 v67, v94, v143
	s_waitcnt lgkmcnt(9)
	v_fmac_f32_e32 v92, v94, v156
	v_fmac_f32_e32 v90, v94, v157
	v_fmac_f32_e32 v87, v94, v158
	v_fmac_f32_e32 v77, v94, v159
	s_waitcnt lgkmcnt(8)
	v_fmac_f32_e32 v76, v94, v144
	v_fmac_f32_e32 v73, v94, v145
	v_fmac_f32_e32 v71, v94, v146
	v_fmac_f32_e32 v64, v94, v147
	ds_read_b128 v[226:229], v104
	ds_read_b128 v[196:199], v105
	ds_read_b128 v[230:233], v106
	ds_read_b128 v[234:237], v107
	s_waitcnt lgkmcnt(11)
	v_fmac_f32_e32 v89, v95, v170
	v_fmac_f32_e32 v88, v95, v171
	v_fmac_f32_e32 v85, v95, v172
	v_fmac_f32_e32 v75, v95, v173
	ds_read_b128 v[148:151], v102 offset:51200
	s_waitcnt lgkmcnt(11)
	v_fmac_f32_e32 v74, v95, v152
	v_fmac_f32_e32 v72, v95, v153
	v_fmac_f32_e32 v70, v95, v154
	v_fmac_f32_e32 v67, v95, v155
	s_waitcnt lgkmcnt(8)
	v_fmac_f32_e32 v89, v58, v182
	v_fmac_f32_e32 v88, v58, v183
	v_fmac_f32_e32 v85, v58, v184
	v_fmac_f32_e32 v75, v58, v185
	ds_read_b128 v[140:143], v102 offset:51216
	v_fmac_f32_e32 v92, v95, v174
	v_fmac_f32_e32 v90, v95, v175
	v_fmac_f32_e32 v87, v95, v176
	v_fmac_f32_e32 v77, v95, v177
	s_waitcnt lgkmcnt(8)
	v_fmac_f32_e32 v74, v58, v188
	v_fmac_f32_e32 v72, v58, v189
	v_fmac_f32_e32 v70, v58, v190
	v_fmac_f32_e32 v67, v58, v191
	ds_read_b128 v[156:159], v102 offset:51232
	v_fmac_f32_e32 v76, v95, v178
	v_fmac_f32_e32 v73, v95, v179
	v_fmac_f32_e32 v71, v95, v180
	v_fmac_f32_e32 v64, v95, v181
	s_waitcnt lgkmcnt(8)
	v_fmac_f32_e32 v92, v58, v222
	v_fmac_f32_e32 v90, v58, v223
	v_fmac_f32_e32 v87, v58, v224
	v_fmac_f32_e32 v77, v58, v225
	ds_read_b128 v[144:147], v102 offset:51248
	s_waitcnt lgkmcnt(8)
	v_fmac_f32_e32 v76, v58, v192
	v_fmac_f32_e32 v73, v58, v193
	v_fmac_f32_e32 v71, v58, v194
	v_fmac_f32_e32 v64, v58, v195
	ds_read_b128 v[170:173], v103 offset:30720
	s_waitcnt lgkmcnt(8)
	v_fmac_f32_e32 v89, v59, v226
	v_fmac_f32_e32 v88, v59, v227
	v_fmac_f32_e32 v85, v59, v228
	v_fmac_f32_e32 v75, v59, v229
	ds_read_b128 v[152:155], v103 offset:30736
	s_waitcnt lgkmcnt(8)
	v_fmac_f32_e32 v74, v59, v196
	v_fmac_f32_e32 v72, v59, v197
	v_fmac_f32_e32 v70, v59, v198
	v_fmac_f32_e32 v67, v59, v199
	ds_read_b128 v[182:185], v103 offset:30752
	s_waitcnt lgkmcnt(8)
	v_fmac_f32_e32 v92, v59, v230
	v_fmac_f32_e32 v90, v59, v231
	v_fmac_f32_e32 v87, v59, v232
	v_fmac_f32_e32 v77, v59, v233
	ds_read_b128 v[174:177], v103 offset:30768
	s_waitcnt lgkmcnt(8)
	v_fmac_f32_e32 v76, v59, v234
	v_fmac_f32_e32 v73, v59, v235
	v_fmac_f32_e32 v71, v59, v236
	v_fmac_f32_e32 v64, v59, v237
	v_pk_mul_f32 v[58:59], v[54:55], v[66:67] op_sel_hi:[1,0]
	v_pk_mul_f32 v[54:55], v[56:57], v[66:67] op_sel_hi:[1,0]
	v_pk_mul_f32 v[94:95], v[10:11], v[58:59]
	v_pk_mul_f32 v[54:55], v[12:13], v[54:55]
	v_cvt_pk_bf16_f32 v56, v94, v95
	s_nop 0
	v_cvt_pk_bf16_f32 v57, v54, v55
	global_store_dwordx2 v[68:69], v[56:57], off offset:1024
	ds_read_b128 v[188:191], v103 offset:51200
	ds_read_b128 v[178:181], v103 offset:51216
	ds_read_b128 v[222:225], v103 offset:51232
	ds_read_b128 v[192:195], v103 offset:51248
	s_waitcnt lgkmcnt(11)
	v_fmac_f32_e32 v89, v94, v148
	v_fmac_f32_e32 v88, v94, v149
	v_fmac_f32_e32 v85, v94, v150
	v_fmac_f32_e32 v75, v94, v151
	s_waitcnt lgkmcnt(10)
	v_fmac_f32_e32 v74, v94, v140
	v_fmac_f32_e32 v72, v94, v141
	v_fmac_f32_e32 v70, v94, v142
	v_fmac_f32_e32 v67, v94, v143
	s_waitcnt lgkmcnt(9)
	v_fmac_f32_e32 v92, v94, v156
	v_fmac_f32_e32 v90, v94, v157
	v_fmac_f32_e32 v87, v94, v158
	v_fmac_f32_e32 v77, v94, v159
	s_waitcnt lgkmcnt(8)
	v_fmac_f32_e32 v76, v94, v144
	v_fmac_f32_e32 v73, v94, v145
	v_fmac_f32_e32 v71, v94, v146
	v_fmac_f32_e32 v64, v94, v147
	ds_read_b128 v[226:229], v108
	ds_read_b128 v[196:199], v109
	ds_read_b128 v[230:233], v110
	ds_read_b128 v[234:237], v111
	s_waitcnt lgkmcnt(11)
	v_fmac_f32_e32 v89, v95, v170
	v_fmac_f32_e32 v88, v95, v171
	v_fmac_f32_e32 v85, v95, v172
	v_fmac_f32_e32 v75, v95, v173
	ds_read_b128 v[148:151], v102 offset:56320
	s_waitcnt lgkmcnt(11)
	v_fmac_f32_e32 v74, v95, v152
	v_fmac_f32_e32 v72, v95, v153
	v_fmac_f32_e32 v70, v95, v154
	v_fmac_f32_e32 v67, v95, v155
	s_waitcnt lgkmcnt(8)
	v_fmac_f32_e32 v89, v54, v188
	v_fmac_f32_e32 v88, v54, v189
	v_fmac_f32_e32 v85, v54, v190
	v_fmac_f32_e32 v75, v54, v191
	ds_read_b128 v[140:143], v102 offset:56336
	v_fmac_f32_e32 v92, v95, v182
	v_fmac_f32_e32 v90, v95, v183
	v_fmac_f32_e32 v87, v95, v184
	v_fmac_f32_e32 v77, v95, v185
	s_waitcnt lgkmcnt(8)
	v_fmac_f32_e32 v74, v54, v178
	v_fmac_f32_e32 v72, v54, v179
	v_fmac_f32_e32 v70, v54, v180
	v_fmac_f32_e32 v67, v54, v181
	ds_read_b128 v[156:159], v102 offset:56352
	v_fmac_f32_e32 v76, v95, v174
	v_fmac_f32_e32 v73, v95, v175
	v_fmac_f32_e32 v71, v95, v176
	v_fmac_f32_e32 v64, v95, v177
	s_waitcnt lgkmcnt(8)
	v_fmac_f32_e32 v92, v54, v222
	v_fmac_f32_e32 v90, v54, v223
	v_fmac_f32_e32 v87, v54, v224
	v_fmac_f32_e32 v77, v54, v225
	ds_read_b128 v[144:147], v102 offset:56368
	s_waitcnt lgkmcnt(8)
	v_fmac_f32_e32 v76, v54, v192
	v_fmac_f32_e32 v73, v54, v193
	v_fmac_f32_e32 v71, v54, v194
	v_fmac_f32_e32 v64, v54, v195
	ds_read_b128 v[170:173], v103 offset:35840
	s_waitcnt lgkmcnt(8)
	v_fmac_f32_e32 v89, v55, v226
	v_fmac_f32_e32 v88, v55, v227
	v_fmac_f32_e32 v85, v55, v228
	v_fmac_f32_e32 v75, v55, v229
	ds_read_b128 v[152:155], v103 offset:35856
	s_waitcnt lgkmcnt(8)
	v_fmac_f32_e32 v74, v55, v196
	v_fmac_f32_e32 v72, v55, v197
	v_fmac_f32_e32 v70, v55, v198
	v_fmac_f32_e32 v67, v55, v199
	ds_read_b128 v[188:191], v103 offset:35872
	s_waitcnt lgkmcnt(8)
; #define LAS __attribute__((address_space(3)))
; __device__ void phase0(const Params& P, LAS unsigned char* lds, const int G, const int bid) {
;     ...
;                   for (int j = 0; j < 4; ++j) { const LAS float* wr_ = wg + (j * 256 + i * 64 + lane) * 20; const float a = v[i][j];
; #pragma unroll
;                       for (int q = 0; q < 4; ++q) { const f32x4 wv = *(const LAS f32x4*)(wr_ + 4 * q);
;                           ga[4 * q] += a * wv[0]; ga[4 * q + 1] += a * wv[1]; ga[4 * q + 2] += a * wv[2]; ga[4 * q + 3] += a * wv[3]; } } }
;               float r8[8], r4[4], r2[2], r1;
; #pragma unroll
;               for (int c = 0; c < 8; ++c) { const bool hi = (lane & 32) != 0; const float send = hi ? ga[c] : ga[c + 8], keep = hi ? ga[c + 8] : ga[c]; r8[c] = keep + __shfl_xor(send, 32); }
; #pragma unroll
;               for (int c = 0; c < 4; ++c) { const bool hi = (lane & 16) != 0; const float send = hi ? r8[c] : r8[c + 4], keep = hi ? r8[c + 4] : r8[c]; r4[c] = keep + __shfl_xor(send, 16); }
; #pragma unroll
;               for (int c = 0; c < 2; ++c) { const bool hi = (lane & 8) != 0; const float send = hi ? r4[c] : r4[c + 2], keep = hi ? r4[c + 2] : r4[c]; r2[c] = keep + __shfl_xor(send, 8); }
;               { const bool hi = (lane & 4) != 0; const float send = hi ? r2[0] : r2[1], keep = hi ? r2[1] : r2[0]; r1 = keep + __shfl_xor(send, 4); }
;               r1 += __shfl_xor(r1, 2); r1 += __shfl_xor(r1, 1);
	v_fmac_f32_e32 v92, v55, v230
	v_fmac_f32_e32 v90, v55, v231
	v_fmac_f32_e32 v87, v55, v232
	v_fmac_f32_e32 v77, v55, v233
	ds_read_b128 v[182:185], v103 offset:35888
	s_waitcnt lgkmcnt(8)
	v_fmac_f32_e32 v76, v55, v234
	v_fmac_f32_e32 v73, v55, v235
	v_fmac_f32_e32 v71, v55, v236
	v_fmac_f32_e32 v64, v55, v237
	v_pk_mul_f32 v[54:55], v[50:51], v[66:67] op_sel_hi:[1,0]
	v_pk_mul_f32 v[50:51], v[52:53], v[66:67] op_sel_hi:[1,0]
	v_pk_mul_f32 v[94:95], v[14:15], v[54:55]
	v_pk_mul_f32 v[50:51], v[16:17], v[50:51]
	v_cvt_pk_bf16_f32 v52, v94, v95
	s_nop 0
	v_cvt_pk_bf16_f32 v53, v50, v51
	global_store_dwordx2 v[68:69], v[52:53], off offset:1536
	ds_read_b128 v[178:181], v103 offset:56320
	ds_read_b128 v[174:177], v103 offset:56336
	ds_read_b128 v[222:225], v103 offset:56352
	ds_read_b128 v[192:195], v103 offset:56368
	s_waitcnt lgkmcnt(11)
	v_fmac_f32_e32 v89, v94, v148
	v_fmac_f32_e32 v88, v94, v149
	v_fmac_f32_e32 v85, v94, v150
	v_fmac_f32_e32 v75, v94, v151
	s_waitcnt lgkmcnt(10)
	v_fmac_f32_e32 v74, v94, v140
	v_fmac_f32_e32 v72, v94, v141
	v_fmac_f32_e32 v70, v94, v142
	v_fmac_f32_e32 v67, v94, v143
	s_waitcnt lgkmcnt(9)
	v_fmac_f32_e32 v92, v94, v156
	v_fmac_f32_e32 v90, v94, v157
	v_fmac_f32_e32 v87, v94, v158
	v_fmac_f32_e32 v77, v94, v159
	s_waitcnt lgkmcnt(8)
	v_fmac_f32_e32 v76, v94, v144
	v_fmac_f32_e32 v73, v94, v145
	v_fmac_f32_e32 v71, v94, v146
	v_fmac_f32_e32 v64, v94, v147
	ds_read_b128 v[226:229], v112
	ds_read_b128 v[196:199], v113
	ds_read_b128 v[230:233], v114
	ds_read_b128 v[234:237], v115
	s_waitcnt lgkmcnt(11)
	v_fmac_f32_e32 v89, v95, v170
	v_fmac_f32_e32 v88, v95, v171
	v_fmac_f32_e32 v85, v95, v172
	v_fmac_f32_e32 v75, v95, v173
	s_waitcnt lgkmcnt(10)
	v_fmac_f32_e32 v74, v95, v152
	v_fmac_f32_e32 v72, v95, v153
	v_fmac_f32_e32 v70, v95, v154
	v_fmac_f32_e32 v67, v95, v155
	s_waitcnt lgkmcnt(7)
	v_fmac_f32_e32 v89, v50, v178
	v_fmac_f32_e32 v88, v50, v179
	v_fmac_f32_e32 v85, v50, v180
	v_fmac_f32_e32 v75, v50, v181
	v_fmac_f32_e32 v92, v95, v188
	v_fmac_f32_e32 v90, v95, v189
	v_fmac_f32_e32 v87, v95, v190
	v_fmac_f32_e32 v77, v95, v191
	s_waitcnt lgkmcnt(6)
	v_fmac_f32_e32 v74, v50, v174
	v_fmac_f32_e32 v72, v50, v175
	v_fmac_f32_e32 v70, v50, v176
	v_fmac_f32_e32 v67, v50, v177
	v_fmac_f32_e32 v76, v95, v182
	v_fmac_f32_e32 v73, v95, v183
	v_fmac_f32_e32 v71, v95, v184
	v_fmac_f32_e32 v64, v95, v185
	s_waitcnt lgkmcnt(5)
	v_fmac_f32_e32 v92, v50, v222
	v_fmac_f32_e32 v90, v50, v223
	v_fmac_f32_e32 v87, v50, v224
	v_fmac_f32_e32 v77, v50, v225
	s_waitcnt lgkmcnt(4)
	v_fmac_f32_e32 v76, v50, v192
	v_fmac_f32_e32 v73, v50, v193
	v_fmac_f32_e32 v71, v50, v194
	v_fmac_f32_e32 v64, v50, v195
	s_waitcnt lgkmcnt(3)
	v_fmac_f32_e32 v89, v51, v226
	v_fmac_f32_e32 v88, v51, v227
	v_fmac_f32_e32 v85, v51, v228
	v_fmac_f32_e32 v75, v51, v229
	s_waitcnt lgkmcnt(2)
	v_fmac_f32_e32 v74, v51, v196
	v_fmac_f32_e32 v72, v51, v197
	v_fmac_f32_e32 v70, v51, v198
	v_fmac_f32_e32 v67, v51, v199
	s_waitcnt lgkmcnt(1)
	v_fmac_f32_e32 v92, v51, v230
	v_fmac_f32_e32 v90, v51, v231
	v_fmac_f32_e32 v87, v51, v232
	v_fmac_f32_e32 v77, v51, v233
	s_waitcnt lgkmcnt(0)
	v_fmac_f32_e32 v76, v51, v234
	v_fmac_f32_e32 v73, v51, v235
	v_fmac_f32_e32 v71, v51, v236
	v_fmac_f32_e32 v64, v51, v237
	v_cndmask_b32_e32 v140, v89, v92, vcc
	v_cndmask_b32_e32 v141, v92, v89, vcc
	v_cndmask_b32_e32 v142, v88, v90, vcc
	v_cndmask_b32_e32 v143, v90, v88, vcc
	v_cndmask_b32_e32 v144, v87, v85, vcc
	v_cndmask_b32_e32 v145, v77, v75, vcc
	v_cndmask_b32_e32 v146, v76, v74, vcc
	v_cndmask_b32_e32 v147, v85, v87, vcc
	v_cndmask_b32_e32 v148, v73, v72, vcc
	v_cndmask_b32_e32 v149, v71, v70, vcc
	v_cndmask_b32_e32 v150, v64, v67, vcc
	v_cndmask_b32_e32 v151, v75, v77, vcc
	v_cndmask_b32_e32 v152, v74, v76, vcc
	v_cndmask_b32_e32 v153, v72, v73, vcc
	v_cndmask_b32_e32 v154, v70, v71, vcc
	v_cndmask_b32_e32 v155, v67, v64, vcc
	ds_bpermute_b32 v156, v96, v140
	ds_bpermute_b32 v157, v96, v142
	ds_bpermute_b32 v158, v96, v147
	ds_bpermute_b32 v159, v96, v151
	ds_bpermute_b32 v170, v96, v152
	ds_bpermute_b32 v171, v96, v153
	ds_bpermute_b32 v172, v96, v154
	ds_bpermute_b32 v173, v96, v155
	s_waitcnt lgkmcnt(7)
	v_add_f32_e32 v174, v141, v156
	s_waitcnt lgkmcnt(6)
	v_add_f32_e32 v175, v143, v157
	s_waitcnt lgkmcnt(5)
	v_add_f32_e32 v176, v144, v158
	s_waitcnt lgkmcnt(4)
	v_add_f32_e32 v177, v145, v159
	s_waitcnt lgkmcnt(3)
	v_add_f32_e32 v178, v146, v170
	s_waitcnt lgkmcnt(2)
	v_add_f32_e32 v55, v148, v171
	s_waitcnt lgkmcnt(1)
	v_add_f32_e32 v56, v149, v172
	s_waitcnt lgkmcnt(0)
	v_add_f32_e32 v57, v150, v173
	v_cndmask_b32_e64 v58, v174, v178, s[42:43]
	v_cndmask_b32_e64 v179, v178, v174, s[42:43]
	v_cndmask_b32_e64 v180, v175, v55, s[42:43]
	v_cndmask_b32_e64 v181, v55, v175, s[42:43]
	v_cndmask_b32_e64 v182, v176, v56, s[42:43]
	v_cndmask_b32_e64 v183, v56, v176, s[42:43]
	v_cndmask_b32_e64 v184, v177, v57, s[42:43]
	v_cndmask_b32_e64 v185, v57, v177, s[42:43]
	ds_bpermute_b32 v188, v97, v58
	ds_bpermute_b32 v189, v97, v180
	ds_bpermute_b32 v190, v97, v182
	ds_bpermute_b32 v191, v97, v184
	s_waitcnt lgkmcnt(3)
	v_add_f32_e32 v192, v179, v188
	s_waitcnt lgkmcnt(2)
	v_add_f32_e32 v193, v181, v189
	s_waitcnt lgkmcnt(1)
	v_add_f32_e32 v194, v183, v190
	s_waitcnt lgkmcnt(0)
	v_add_f32_e32 v53, v185, v191
	v_cndmask_b32_e64 v54, v192, v194, s[44:45]
	v_cndmask_b32_e64 v195, v194, v192, s[44:45]
	v_cndmask_b32_e64 v196, v193, v53, s[44:45]
	v_cndmask_b32_e64 v197, v53, v193, s[44:45]
	ds_bpermute_b32 v198, v98, v54
	ds_bpermute_b32 v199, v98, v196
	s_waitcnt lgkmcnt(1)
	v_add_f32_e32 v222, v195, v198
	s_waitcnt lgkmcnt(0)
	v_add_f32_e32 v223, v197, v199
	v_cndmask_b32_e64 v52, v222, v223, s[46:47]
	v_cndmask_b32_e64 v224, v223, v222, s[46:47]
	ds_bpermute_b32 v225, v99, v52
	s_waitcnt lgkmcnt(0)
	v_add_f32_e32 v226, v224, v225
	ds_bpermute_b32 v227, v100, v226
	s_waitcnt lgkmcnt(0)
	v_add_f32_e32 v50, v226, v227
	ds_bpermute_b32 v51, v101, v50
	s_and_b64 exec, exec, s[48:49]
	s_cbranch_execz .LBB0_1055
; __device__ __forceinline__ float logsigmoidf_(float x) { return fminf(x, 0.0f) - log1pf(__expf(-fabsf(x))); }
; __device__ void phase0(const Params& P, LAS unsigned char* lds, const int G, const int bid) {
;     ...
;               if ((lane & 3) == 0) { float gv = r1 + gbias; if (gcol >= 8) gv = logsigmoidf_(gv); gates[(size_t)row * 16 + gcol] = gv; }
	s_waitcnt lgkmcnt(0)
	v_add_f32_e32 v50, v50, v51
	v_add_f32_e32 v50, v91, v50
	s_and_saveexec_b64 s[8:9], s[40:41]
	s_cbranch_execz .LBB0_1054
	s_mov_b32 s12, 0xbfb8aa3b
	v_mul_f32_e64 v51, |v50|, s12
	v_exp_f32_e32 v64, v51
	v_max_f32_e32 v50, v50, v50
	v_min_f32_e32 v65, 0, v50
	s_mov_b32 s12, 0x3f2aaaab
	v_add_f32_e32 v52, 1.0, v64
	v_add_f32_e32 v50, -1.0, v52
	v_sub_f32_e32 v51, v50, v52
	v_sub_f32_e32 v50, v64, v50
	v_add_f32_e32 v51, 1.0, v51
	v_add_f32_e32 v53, v50, v51
	v_frexp_mant_f32_e32 v54, v52
	v_cvt_f64_f32_e32 v[50:51], v52
	v_frexp_exp_i32_f64_e32 v50, v[50:51]
	v_cmp_gt_f32_e64 s[50:51], s12, v54
	s_mov_b32 s12, 0x3f317218
	s_nop 0
	v_subbrev_co_u32_e64 v58, s[50:51], 0, v50, s[50:51]
	v_sub_u32_e32 v50, 0, v58
	v_ldexp_f32 v51, v52, v50
	v_add_f32_e32 v52, -1.0, v51
	v_add_f32_e32 v54, 1.0, v51
	v_ldexp_f32 v50, v53, v50
	v_add_f32_e32 v53, 1.0, v52
	v_add_f32_e32 v55, -1.0, v54
	v_sub_f32_e32 v53, v51, v53
	v_sub_f32_e32 v51, v51, v55
	v_add_f32_e32 v53, v50, v53
	v_add_f32_e32 v50, v50, v51
	v_add_f32_e32 v59, v54, v50
	v_rcp_f32_e32 v61, v59
	v_sub_f32_e32 v51, v59, v54
	v_sub_f32_e32 v60, v50, v51
	v_add_f32_e32 v51, v52, v53
	v_mul_f32_e32 v63, v51, v61
	v_sub_f32_e32 v50, v51, v52
	v_mul_f32_e32 v52, v59, v63
	v_fma_f32 v54, v63, v59, -v52
	v_fmac_f32_e32 v54, v63, v60
	v_sub_f32_e32 v62, v53, v50
	v_add_f32_e32 v50, v52, v54
	v_sub_f32_e32 v53, v51, v50
	v_pk_add_f32 v[56:57], v[50:51], v[52:53] neg_lo:[0,1] neg_hi:[0,1]
	v_mov_b32_e32 v55, v50
	v_pk_add_f32 v[50:51], v[56:57], v[54:55] neg_lo:[0,1] neg_hi:[0,1]
	s_nop 0
	v_add_f32_e32 v51, v62, v51
	v_add_f32_e32 v50, v50, v51
	v_add_f32_e32 v51, v53, v50
	v_mul_f32_e32 v62, v61, v51
	v_mul_f32_e32 v52, v59, v62
	v_fma_f32 v54, v62, v59, -v52
	v_fmac_f32_e32 v54, v62, v60
	v_sub_f32_e32 v53, v53, v51
	v_add_f32_e32 v59, v50, v53
	v_add_f32_e32 v50, v52, v54
	v_sub_f32_e32 v53, v51, v50
	v_pk_add_f32 v[56:57], v[50:51], v[52:53] neg_lo:[0,1] neg_hi:[0,1]
	v_mov_b32_e32 v55, v50
	v_pk_add_f32 v[50:51], v[56:57], v[54:55] neg_lo:[0,1] neg_hi:[0,1]
	s_nop 0
	v_add_f32_e32 v51, v59, v51
	v_add_f32_e32 v50, v50, v51
	v_add_f32_e32 v51, v63, v62
	v_add_f32_e32 v50, v53, v50
	v_sub_f32_e32 v52, v51, v63
	v_mul_f32_e32 v50, v61, v50
	v_sub_f32_e32 v52, v62, v52
	v_add_f32_e32 v52, v52, v50
	v_add_f32_e32 v54, v51, v52
	v_mul_f32_e32 v55, v54, v54
	v_fmamk_f32 v50, v55, 0x3e9b6dac, v208
	v_fmaak_f32 v169, v55, v50, 0x3f2aaada
	v_cvt_f32_i32_e32 v50, v58
	v_sub_f32_e32 v51, v54, v51
	v_sub_f32_e32 v51, v52, v51
	v_ldexp_f32 v56, v51, 1
	v_mul_f32_e32 v51, v54, v55
	v_ldexp_f32 v53, v54, 1
	v_pk_mul_f32 v[54:55], v[50:51], v[168:169]
	s_nop 0
	v_fma_f32 v52, v50, s12, -v54
	v_fmac_f32_e32 v52, 0xb102e308, v50
	v_pk_add_f32 v[50:51], v[54:55], v[52:53]
	s_mov_b32 s12, 0x7f800000
	v_sub_f32_e32 v53, v51, v53
	v_sub_f32_e32 v53, v55, v53
	v_add_f32_e32 v57, v56, v53
	v_mov_b32_e32 v56, v54
	v_pk_add_f32 v[54:55], v[50:51], v[54:55] neg_lo:[0,1] neg_hi:[0,1]
	v_pk_add_f32 v[58:59], v[50:51], v[56:57]
	v_mov_b32_e32 v53, v50
	v_mov_b32_e32 v55, v59
	v_pk_add_f32 v[60:61], v[52:53], v[54:55] neg_lo:[0,1] neg_hi:[0,1]
	v_pk_add_f32 v[52:53], v[52:53], v[54:55]
	v_mov_b32_e32 v56, v57
	v_pk_add_f32 v[54:55], v[52:53], v[50:51] op_sel:[1,0] op_sel_hi:[0,1] neg_lo:[0,1] neg_hi:[0,1]
	s_nop 0
	v_pk_add_f32 v[62:63], v[58:59], v[54:55] op_sel_hi:[1,0] neg_lo:[0,1] neg_hi:[0,1]
	v_mov_b32_e32 v58, v59
	v_mov_b32_e32 v59, v53
	v_pk_mov_b32 v[54:55], v[50:51], v[54:55] op_sel:[1,0]
	v_mov_b32_e32 v57, v50
	v_pk_add_f32 v[54:55], v[58:59], v[54:55] neg_lo:[0,1] neg_hi:[0,1]
	v_mov_b32_e32 v62, v60
	v_pk_add_f32 v[50:51], v[56:57], v[54:55] neg_lo:[0,1] neg_hi:[0,1]
	v_mov_b32_e32 v61, v53
	v_pk_add_f32 v[54:55], v[62:63], v[50:51]
	v_cmp_neq_f32_e64 s[50:51], s12, v64
	v_pk_add_f32 v[56:57], v[54:55], v[54:55] op_sel:[0,1] op_sel_hi:[1,0]
	s_mov_b32 s12, 0x33800000
	v_pk_add_f32 v[52:53], v[52:53], v[56:57] op_sel:[1,0] op_sel_hi:[0,1]
	s_nop 0
	v_mov_b32_e32 v55, v52
	v_pk_add_f32 v[58:59], v[54:55], v[60:61] neg_lo:[0,1] neg_hi:[0,1]
	v_mov_b32_e32 v51, v56
	v_sub_f32_e32 v53, v54, v58
	v_pk_add_f32 v[50:51], v[50:51], v[58:59] neg_lo:[0,1] neg_hi:[0,1]
	v_sub_f32_e32 v53, v60, v53
	v_add_f32_e32 v50, v50, v53
	v_add_f32_e32 v50, v50, v51
	v_add_f32_e32 v50, v52, v50
	v_cndmask_b32_e64 v50, v212, v50, s[50:51]
	v_cmp_ngt_f32_e64 s[50:51], -1.0, v64
	s_nop 1
	v_cndmask_b32_e64 v50, v213, v50, s[50:51]
	v_cmp_neq_f32_e64 s[50:51], -1.0, v64
	s_nop 1
	v_cndmask_b32_e64 v50, v214, v50, s[50:51]
	v_cmp_lt_f32_e64 s[50:51], |v64|, s12
	s_nop 1
	v_cndmask_b32_e64 v50, v50, v64, s[50:51]
	v_sub_f32_e32 v50, v65, v50

; #define LAS __attribute__((address_space(3)))
; __device__ __forceinline__ unsigned cvt_pk_bf16(float lo, float hi) { unsigned r; asm volatile("v_cvt_pk_bf16_f32 %0, %1, %2" : "=v"(r) : "v"(lo), "v"(hi)); return r; }
; __device__ void phase0(const Params& P, LAS unsigned char* lds, const int G, const int bid) {
;     ...
;           for (int rr = 0; rr < 4; ++rr) { const int row = row0 + rr * G * 8; if (row >= NTOK) continue;
;               f32x4 (&v)[4] = vv[rr]; float ss = 0.f;
; #pragma unroll
;               for (int i = 0; i < 4; ++i)
; #pragma unroll
;                   for (int j = 0; j < 4; ++j) ss += v[i][j] * v[i][j];
; #pragma unroll
;               for (int o = 32; o >= 1; o >>= 1) ss += __shfl_xor(ss, o);
;               const float rstd = rsqrtf(ss * (1.0f / DM) + 1e-6f);
;               float ga[16];
; #pragma unroll
;               for (int c = 0; c < 16; ++c) ga[c] = 0.f;
; #pragma unroll
;               for (int i = 0; i < 4; ++i) { v[i] = v[i] * rstd * w4[i];
;                   u32x2 w; w.x = cvt_pk_bf16(v[i][0], v[i][1]); w.y = cvt_pk_bf16(v[i][2], v[i][3]);
;                   *(u32x2*)(abf + (size_t)row * DM + 4 * lane + 256 * i) = w;
; #pragma unroll
;                   for (int j = 0; j < 4; ++j) { const LAS float* wr_ = wg + (j * 256 + i * 64 + lane) * 20; const float a = v[i][j];
; #pragma unroll
;                       for (int q = 0; q < 4; ++q) { const f32x4 wv = *(const LAS f32x4*)(wr_ + 4 * q);
;                           ga[4 * q] += a * wv[0]; ga[4 * q + 1] += a * wv[1]; ga[4 * q + 2] += a * wv[2]; ga[4 * q + 3] += a * wv[3]; } } }
.LBB0_1055:
	s_or_b64 exec, exec, s[6:7]
	v_cmp_gt_i32_e64 s[50:51], s15, v86
	s_and_saveexec_b64 s[6:7], s[50:51]
	s_cbranch_execz .LBB0_1060
	s_waitcnt vmcnt(11)
	v_mul_f32_e32 v54, v47, v47
	v_fmac_f32_e32 v54, v46, v46
	v_fmac_f32_e32 v54, v48, v48
	v_fmac_f32_e32 v54, v49, v49
	s_waitcnt vmcnt(10)
	v_fmac_f32_e32 v54, v42, v42
	v_fmac_f32_e32 v54, v43, v43
	v_fmac_f32_e32 v54, v44, v44
	v_fmac_f32_e32 v54, v45, v45
	s_waitcnt vmcnt(9)
	v_fmac_f32_e32 v54, v38, v38
	v_fmac_f32_e32 v54, v39, v39
	v_fmac_f32_e32 v54, v40, v40
	v_fmac_f32_e32 v54, v41, v41
	s_waitcnt vmcnt(8)
	v_pk_mul_f32 v[52:53], v[34:35], v[34:35]
	s_waitcnt lgkmcnt(0)
	v_pk_mul_f32 v[50:51], v[36:37], v[36:37]
	v_add_f32_e32 v52, v52, v54
	v_add_f32_e32 v52, v53, v52
	v_add_f32_e32 v50, v50, v52
	v_add_f32_e32 v50, v51, v50
	ds_bpermute_b32 v51, v96, v50
	v_ashrrev_i32_e32 v87, 31, v86
	v_lshlrev_b64 v[52:53], 11, v[86:87]
	v_lshl_add_u64 v[52:53], v[80:81], 0, v[52:53]
	s_waitcnt lgkmcnt(0)
	v_add_f32_e32 v50, v50, v51
	ds_bpermute_b32 v51, v97, v50
	s_waitcnt lgkmcnt(0)
	v_add_f32_e32 v50, v50, v51
	ds_bpermute_b32 v51, v98, v50
	s_waitcnt lgkmcnt(0)
	v_add_f32_e32 v50, v50, v51
	ds_bpermute_b32 v51, v99, v50
	s_waitcnt lgkmcnt(0)
	v_add_f32_e32 v50, v50, v51
	ds_bpermute_b32 v51, v100, v50
	s_waitcnt lgkmcnt(0)
	v_add_f32_e32 v50, v50, v51
	ds_bpermute_b32 v51, v101, v50
	s_waitcnt lgkmcnt(0)
	v_add_f32_e32 v50, v50, v51
	v_fmamk_f32 v50, v50, 0x3a800000, v210
	v_cmp_gt_f32_e64 s[50:51], s30, v50
	v_mul_f32_e32 v51, 0x4b800000, v50
	s_nop 0
	v_cndmask_b32_e64 v50, v50, v51, s[50:51]
	v_rsq_f32_e32 v50, v50
	s_nop 0
	v_mul_f32_e32 v51, 0x45800000, v50
	v_cndmask_b32_e64 v50, v50, v51, s[50:51]
	v_pk_mul_f32 v[54:55], v[46:47], v[50:51] op_sel_hi:[1,0]
	v_pk_mul_f32 v[46:47], v[48:49], v[50:51] op_sel_hi:[1,0]
	v_pk_mul_f32 v[48:49], v[2:3], v[54:55]
	v_pk_mul_f32 v[46:47], v[4:5], v[46:47]
	v_cvt_pk_bf16_f32 v54, v48, v49
	s_nop 0
	v_cvt_pk_bf16_f32 v55, v46, v47
	global_store_dwordx2 v[52:53], v[54:55], off
	ds_read_b128 v[140:143], v102 offset:40960
	ds_read_b128 v[144:147], v102 offset:40976
	ds_read_b128 v[148:151], v102 offset:40992
	ds_read_b128 v[152:155], v102 offset:41008
	ds_read_b128 v[156:159], v102 offset:61440
	ds_read_b128 v[170:173], v102 offset:61456
	ds_read_b128 v[174:177], v102 offset:61472
	ds_read_b128 v[178:181], v102 offset:61488
	ds_read_b128 v[182:185], v103 offset:40960
	ds_read_b128 v[188:191], v103 offset:40976
	ds_read_b128 v[192:195], v103 offset:40992
	ds_read_b128 v[196:199], v103 offset:41008
	s_waitcnt lgkmcnt(11)
	v_fma_f32 v65, v140, v48, 0
	v_fma_f32 v62, v142, v48, 0
	s_waitcnt lgkmcnt(10)
	v_fma_f32 v58, v144, v48, 0
	v_fma_f32 v56, v145, v48, 0
	v_fma_f32 v54, v146, v48, 0
	v_fma_f32 v51, v147, v48, 0
	s_waitcnt lgkmcnt(9)
	v_fma_f32 v67, v148, v48, 0
	v_fma_f32 v66, v149, v48, 0
	ds_read_b128 v[222:225], v103 offset:61440
	v_fma_f32 v64, v141, v48, 0
	v_fma_f32 v59, v143, v48, 0
	v_fma_f32 v63, v150, v48, 0
	v_fma_f32 v61, v151, v48, 0
	s_waitcnt lgkmcnt(8)
	v_fmac_f32_e32 v65, v156, v49
	v_fmac_f32_e32 v64, v157, v49
	v_fmac_f32_e32 v62, v158, v49
	v_fmac_f32_e32 v59, v159, v49
	ds_read_b128 v[226:229], v103 offset:61456
	v_fma_f32 v60, v152, v48, 0
	v_fma_f32 v57, v153, v48, 0
	v_fma_f32 v55, v154, v48, 0
	v_fma_f32 v48, v155, v48, 0
	s_waitcnt lgkmcnt(8)
	v_fmac_f32_e32 v58, v170, v49
	v_fmac_f32_e32 v56, v171, v49
	v_fmac_f32_e32 v54, v172, v49
	v_fmac_f32_e32 v51, v173, v49
	ds_read_b128 v[230:233], v103 offset:61472
	s_waitcnt lgkmcnt(8)
	v_fmac_f32_e32 v67, v174, v49
	v_fmac_f32_e32 v66, v175, v49
	v_fmac_f32_e32 v63, v176, v49
	v_fmac_f32_e32 v61, v177, v49
	ds_read_b128 v[234:237], v103 offset:61488
	s_waitcnt lgkmcnt(8)
	v_fmac_f32_e32 v60, v178, v49
	v_fmac_f32_e32 v57, v179, v49
	v_fmac_f32_e32 v55, v180, v49
	v_fmac_f32_e32 v48, v181, v49
	ds_read_b128 v[144:147], v102 offset:46080
	ds_read_b128 v[140:143], v102 offset:46096
	ds_read_b128 v[148:151], v102 offset:46112
	ds_read_b128 v[156:159], v102 offset:46128
	s_waitcnt lgkmcnt(11)
	v_fmac_f32_e32 v65, v182, v46
	v_fmac_f32_e32 v64, v183, v46
	v_fmac_f32_e32 v62, v184, v46
	v_fmac_f32_e32 v59, v185, v46
	ds_read_b128 v[152:155], v103 offset:25600
	s_waitcnt lgkmcnt(11)
	v_fmac_f32_e32 v58, v46, v188
	v_fmac_f32_e32 v56, v46, v189
	v_fmac_f32_e32 v54, v46, v190
	v_fmac_f32_e32 v51, v46, v191
	s_waitcnt lgkmcnt(8)
	v_fmac_f32_e32 v65, v47, v222
	v_fmac_f32_e32 v64, v47, v223
	v_fmac_f32_e32 v62, v47, v224
	v_fmac_f32_e32 v59, v47, v225
	ds_read_b128 v[170:173], v103 offset:25616
	v_fmac_f32_e32 v67, v46, v192
	v_fmac_f32_e32 v66, v46, v193
	v_fmac_f32_e32 v63, v46, v194
	v_fmac_f32_e32 v61, v46, v195
	s_waitcnt lgkmcnt(8)
	v_fmac_f32_e32 v58, v47, v226
	v_fmac_f32_e32 v56, v47, v227
	v_fmac_f32_e32 v54, v47, v228
	v_fmac_f32_e32 v51, v47, v229
	ds_read_b128 v[174:177], v103 offset:25632
	v_fmac_f32_e32 v60, v46, v196
	v_fmac_f32_e32 v57, v46, v197
	v_fmac_f32_e32 v55, v46, v198
	v_fmac_f32_e32 v48, v46, v199
	s_waitcnt lgkmcnt(8)
	v_fmac_f32_e32 v67, v47, v230
	v_fmac_f32_e32 v66, v47, v231
	v_fmac_f32_e32 v63, v47, v232
	v_fmac_f32_e32 v61, v47, v233
	ds_read_b128 v[178:181], v103 offset:25648
	s_waitcnt lgkmcnt(8)
	v_fmac_f32_e32 v60, v47, v234
	v_fmac_f32_e32 v57, v47, v235
	v_fmac_f32_e32 v55, v47, v236
	v_fmac_f32_e32 v48, v47, v237
	v_pk_mul_f32 v[46:47], v[42:43], v[50:51] op_sel_hi:[1,0]
	v_pk_mul_f32 v[42:43], v[44:45], v[50:51] op_sel_hi:[1,0]
	v_pk_mul_f32 v[76:77], v[6:7], v[46:47]
	v_pk_mul_f32 v[42:43], v[8:9], v[42:43]
	v_cvt_pk_bf16_f32 v44, v76, v77
	s_nop 0
	v_cvt_pk_bf16_f32 v45, v42, v43
	global_store_dwordx2 v[52:53], v[44:45], off offset:512
	ds_read_b128 v[182:185], v103 offset:46080
	ds_read_b128 v[188:191], v103 offset:46096
	ds_read_b128 v[222:225], v103 offset:46112
	ds_read_b128 v[192:195], v103 offset:46128
	s_waitcnt lgkmcnt(11)
; #define LAS __attribute__((address_space(3)))
; __device__ __forceinline__ unsigned cvt_pk_bf16(float lo, float hi) { unsigned r; asm volatile("v_cvt_pk_bf16_f32 %0, %1, %2" : "=v"(r) : "v"(lo), "v"(hi)); return r; }
; __device__ void phase0(const Params& P, LAS unsigned char* lds, const int G, const int bid) {
;     ...
;               for (int i = 0; i < 4; ++i) { v[i] = v[i] * rstd * w4[i];
;                   u32x2 w; w.x = cvt_pk_bf16(v[i][0], v[i][1]); w.y = cvt_pk_bf16(v[i][2], v[i][3]);
;                   *(u32x2*)(abf + (size_t)row * DM + 4 * lane + 256 * i) = w;
; #pragma unroll
;                   for (int j = 0; j < 4; ++j) { const LAS float* wr_ = wg + (j * 256 + i * 64 + lane) * 20; const float a = v[i][j];
; #pragma unroll
;                       for (int q = 0; q < 4; ++q) { const f32x4 wv = *(const LAS f32x4*)(wr_ + 4 * q);
;                           ga[4 * q] += a * wv[0]; ga[4 * q + 1] += a * wv[1]; ga[4 * q + 2] += a * wv[2]; ga[4 * q + 3] += a * wv[3]; } } }
	v_fmac_f32_e32 v65, v76, v144
	v_fmac_f32_e32 v64, v76, v145
	v_fmac_f32_e32 v62, v76, v146
	v_fmac_f32_e32 v59, v76, v147
	s_waitcnt lgkmcnt(10)
	v_fmac_f32_e32 v58, v76, v140
	v_fmac_f32_e32 v56, v76, v141
	v_fmac_f32_e32 v54, v76, v142
	v_fmac_f32_e32 v51, v76, v143
	s_waitcnt lgkmcnt(9)
	v_fmac_f32_e32 v67, v76, v148
	v_fmac_f32_e32 v66, v76, v149
	v_fmac_f32_e32 v63, v76, v150
	v_fmac_f32_e32 v61, v76, v151
	s_waitcnt lgkmcnt(8)
	v_fmac_f32_e32 v60, v76, v156
	v_fmac_f32_e32 v57, v76, v157
	v_fmac_f32_e32 v55, v76, v158
	v_fmac_f32_e32 v48, v76, v159
	ds_read_b128 v[226:229], v104
	ds_read_b128 v[196:199], v105
	ds_read_b128 v[230:233], v106
	ds_read_b128 v[234:237], v107
	s_waitcnt lgkmcnt(11)
	v_fmac_f32_e32 v65, v77, v152
	v_fmac_f32_e32 v64, v77, v153
	v_fmac_f32_e32 v62, v77, v154
	v_fmac_f32_e32 v59, v77, v155
	ds_read_b128 v[144:147], v102 offset:51200
	s_waitcnt lgkmcnt(11)
	v_fmac_f32_e32 v58, v77, v170
	v_fmac_f32_e32 v56, v77, v171
	v_fmac_f32_e32 v54, v77, v172
	v_fmac_f32_e32 v51, v77, v173
	s_waitcnt lgkmcnt(8)
	v_fmac_f32_e32 v65, v42, v182
	v_fmac_f32_e32 v64, v42, v183
	v_fmac_f32_e32 v62, v42, v184
	v_fmac_f32_e32 v59, v42, v185
	ds_read_b128 v[140:143], v102 offset:51216
	v_fmac_f32_e32 v67, v77, v174
	v_fmac_f32_e32 v66, v77, v175
	v_fmac_f32_e32 v63, v77, v176
	v_fmac_f32_e32 v61, v77, v177
	s_waitcnt lgkmcnt(8)
	v_fmac_f32_e32 v58, v42, v188
	v_fmac_f32_e32 v56, v42, v189
	v_fmac_f32_e32 v54, v42, v190
	v_fmac_f32_e32 v51, v42, v191
	ds_read_b128 v[148:151], v102 offset:51232
	v_fmac_f32_e32 v60, v77, v178
	v_fmac_f32_e32 v57, v77, v179
	v_fmac_f32_e32 v55, v77, v180
	v_fmac_f32_e32 v48, v77, v181
	s_waitcnt lgkmcnt(8)
	v_fmac_f32_e32 v67, v42, v222
	v_fmac_f32_e32 v66, v42, v223
	v_fmac_f32_e32 v63, v42, v224
	v_fmac_f32_e32 v61, v42, v225
	ds_read_b128 v[156:159], v102 offset:51248
	s_waitcnt lgkmcnt(8)
	v_fmac_f32_e32 v60, v42, v192
	v_fmac_f32_e32 v57, v42, v193
	v_fmac_f32_e32 v55, v42, v194
	v_fmac_f32_e32 v48, v42, v195
	ds_read_b128 v[152:155], v103 offset:30720
	s_waitcnt lgkmcnt(8)
	v_fmac_f32_e32 v65, v43, v226
	v_fmac_f32_e32 v64, v43, v227
	v_fmac_f32_e32 v62, v43, v228
	v_fmac_f32_e32 v59, v43, v229
	ds_read_b128 v[170:173], v103 offset:30736
	s_waitcnt lgkmcnt(8)
	v_fmac_f32_e32 v58, v43, v196
	v_fmac_f32_e32 v56, v43, v197
	v_fmac_f32_e32 v54, v43, v198
	v_fmac_f32_e32 v51, v43, v199
	ds_read_b128 v[182:185], v103 offset:30752
	s_waitcnt lgkmcnt(8)
	v_fmac_f32_e32 v67, v43, v230
	v_fmac_f32_e32 v66, v43, v231
	v_fmac_f32_e32 v63, v43, v232
	v_fmac_f32_e32 v61, v43, v233
	ds_read_b128 v[174:177], v103 offset:30768
	s_waitcnt lgkmcnt(8)
	v_fmac_f32_e32 v60, v43, v234
	v_fmac_f32_e32 v57, v43, v235
	v_fmac_f32_e32 v55, v43, v236
	v_fmac_f32_e32 v48, v43, v237
	v_pk_mul_f32 v[42:43], v[38:39], v[50:51] op_sel_hi:[1,0]
	v_pk_mul_f32 v[38:39], v[40:41], v[50:51] op_sel_hi:[1,0]
	v_pk_mul_f32 v[76:77], v[10:11], v[42:43]
	v_pk_mul_f32 v[38:39], v[12:13], v[38:39]
	v_cvt_pk_bf16_f32 v40, v76, v77
	s_nop 0
	v_cvt_pk_bf16_f32 v41, v38, v39
	global_store_dwordx2 v[52:53], v[40:41], off offset:1024
	ds_read_b128 v[188:191], v103 offset:51200
	ds_read_b128 v[178:181], v103 offset:51216
	ds_read_b128 v[222:225], v103 offset:51232
	ds_read_b128 v[192:195], v103 offset:51248
	s_waitcnt lgkmcnt(11)
	v_fmac_f32_e32 v65, v76, v144
	v_fmac_f32_e32 v64, v76, v145
	v_fmac_f32_e32 v62, v76, v146
	v_fmac_f32_e32 v59, v76, v147
	s_waitcnt lgkmcnt(10)
	v_fmac_f32_e32 v58, v76, v140
	v_fmac_f32_e32 v56, v76, v141
	v_fmac_f32_e32 v54, v76, v142
	v_fmac_f32_e32 v51, v76, v143
	s_waitcnt lgkmcnt(9)
	v_fmac_f32_e32 v67, v76, v148
	v_fmac_f32_e32 v66, v76, v149
	v_fmac_f32_e32 v63, v76, v150
	v_fmac_f32_e32 v61, v76, v151
	s_waitcnt lgkmcnt(8)
	v_fmac_f32_e32 v60, v76, v156
	v_fmac_f32_e32 v57, v76, v157
	v_fmac_f32_e32 v55, v76, v158
	v_fmac_f32_e32 v48, v76, v159
	ds_read_b128 v[226:229], v108
	ds_read_b128 v[196:199], v109
	ds_read_b128 v[230:233], v110
	ds_read_b128 v[234:237], v111
	s_waitcnt lgkmcnt(11)
	v_fmac_f32_e32 v65, v77, v152
	v_fmac_f32_e32 v64, v77, v153
	v_fmac_f32_e32 v62, v77, v154
	v_fmac_f32_e32 v59, v77, v155
	ds_read_b128 v[144:147], v102 offset:56320
	s_waitcnt lgkmcnt(11)
	v_fmac_f32_e32 v58, v77, v170
	v_fmac_f32_e32 v56, v77, v171
	v_fmac_f32_e32 v54, v77, v172
	v_fmac_f32_e32 v51, v77, v173
	s_waitcnt lgkmcnt(8)
	v_fmac_f32_e32 v65, v38, v188
	v_fmac_f32_e32 v64, v38, v189
	v_fmac_f32_e32 v62, v38, v190
	v_fmac_f32_e32 v59, v38, v191
	ds_read_b128 v[140:143], v102 offset:56336
	v_fmac_f32_e32 v67, v77, v182
	v_fmac_f32_e32 v66, v77, v183
	v_fmac_f32_e32 v63, v77, v184
	v_fmac_f32_e32 v61, v77, v185
	s_waitcnt lgkmcnt(8)
	v_fmac_f32_e32 v58, v38, v178
	v_fmac_f32_e32 v56, v38, v179
	v_fmac_f32_e32 v54, v38, v180
	v_fmac_f32_e32 v51, v38, v181
	ds_read_b128 v[148:151], v102 offset:56352
	v_fmac_f32_e32 v60, v77, v174
	v_fmac_f32_e32 v57, v77, v175
	v_fmac_f32_e32 v55, v77, v176
	v_fmac_f32_e32 v48, v77, v177
	s_waitcnt lgkmcnt(8)
	v_fmac_f32_e32 v67, v38, v222
	v_fmac_f32_e32 v66, v38, v223
	v_fmac_f32_e32 v63, v38, v224
	v_fmac_f32_e32 v61, v38, v225
	ds_read_b128 v[156:159], v102 offset:56368
	s_waitcnt lgkmcnt(8)
	v_fmac_f32_e32 v60, v38, v192
	v_fmac_f32_e32 v57, v38, v193
	v_fmac_f32_e32 v55, v38, v194
	v_fmac_f32_e32 v48, v38, v195
	ds_read_b128 v[152:155], v103 offset:35840
	s_waitcnt lgkmcnt(8)
	v_fmac_f32_e32 v65, v39, v226
	v_fmac_f32_e32 v64, v39, v227
	v_fmac_f32_e32 v62, v39, v228
	v_fmac_f32_e32 v59, v39, v229
	ds_read_b128 v[170:173], v103 offset:35856
	s_waitcnt lgkmcnt(8)
	v_fmac_f32_e32 v58, v39, v196
	v_fmac_f32_e32 v56, v39, v197
	v_fmac_f32_e32 v54, v39, v198
	v_fmac_f32_e32 v51, v39, v199
	ds_read_b128 v[188:191], v103 offset:35872
	s_waitcnt lgkmcnt(8)
; #define LAS __attribute__((address_space(3)))
; __device__ __forceinline__ unsigned cvt_pk_bf16(float lo, float hi) { unsigned r; asm volatile("v_cvt_pk_bf16_f32 %0, %1, %2" : "=v"(r) : "v"(lo), "v"(hi)); return r; }
; __device__ void phase0(const Params& P, LAS unsigned char* lds, const int G, const int bid) {
;     ...
;               for (int i = 0; i < 4; ++i) { v[i] = v[i] * rstd * w4[i];
;                   u32x2 w; w.x = cvt_pk_bf16(v[i][0], v[i][1]); w.y = cvt_pk_bf16(v[i][2], v[i][3]);
;                   *(u32x2*)(abf + (size_t)row * DM + 4 * lane + 256 * i) = w;
; #pragma unroll
;                   for (int j = 0; j < 4; ++j) { const LAS float* wr_ = wg + (j * 256 + i * 64 + lane) * 20; const float a = v[i][j];
; #pragma unroll
;                       for (int q = 0; q < 4; ++q) { const f32x4 wv = *(const LAS f32x4*)(wr_ + 4 * q);
;                           ga[4 * q] += a * wv[0]; ga[4 * q + 1] += a * wv[1]; ga[4 * q + 2] += a * wv[2]; ga[4 * q + 3] += a * wv[3]; } } }
;               float r8[8], r4[4], r2[2], r1;
; #pragma unroll
;               for (int c = 0; c < 8; ++c) { const bool hi = (lane & 32) != 0; const float send = hi ? ga[c] : ga[c + 8], keep = hi ? ga[c + 8] : ga[c]; r8[c] = keep + __shfl_xor(send, 32); }
; #pragma unroll
;               for (int c = 0; c < 4; ++c) { const bool hi = (lane & 16) != 0; const float send = hi ? r8[c] : r8[c + 4], keep = hi ? r8[c + 4] : r8[c]; r4[c] = keep + __shfl_xor(send, 16); }
; #pragma unroll
;               for (int c = 0; c < 2; ++c) { const bool hi = (lane & 8) != 0; const float send = hi ? r4[c] : r4[c + 2], keep = hi ? r4[c + 2] : r4[c]; r2[c] = keep + __shfl_xor(send, 8); }
;               { const bool hi = (lane & 4) != 0; const float send = hi ? r2[0] : r2[1], keep = hi ? r2[1] : r2[0]; r1 = keep + __shfl_xor(send, 4); }
;               r1 += __shfl_xor(r1, 2); r1 += __shfl_xor(r1, 1);
	v_fmac_f32_e32 v67, v39, v230
	v_fmac_f32_e32 v66, v39, v231
	v_fmac_f32_e32 v63, v39, v232
	v_fmac_f32_e32 v61, v39, v233
	ds_read_b128 v[182:185], v103 offset:35888
	s_waitcnt lgkmcnt(8)
	v_fmac_f32_e32 v60, v39, v234
	v_fmac_f32_e32 v57, v39, v235
	v_fmac_f32_e32 v55, v39, v236
	v_fmac_f32_e32 v48, v39, v237
	v_pk_mul_f32 v[38:39], v[34:35], v[50:51] op_sel_hi:[1,0]
	v_pk_mul_f32 v[34:35], v[36:37], v[50:51] op_sel_hi:[1,0]
	v_pk_mul_f32 v[72:73], v[14:15], v[38:39]
	v_pk_mul_f32 v[34:35], v[16:17], v[34:35]
	v_cvt_pk_bf16_f32 v36, v72, v73
	s_nop 0
	v_cvt_pk_bf16_f32 v37, v34, v35
	global_store_dwordx2 v[52:53], v[36:37], off offset:1536
	ds_read_b128 v[178:181], v103 offset:56320
	ds_read_b128 v[174:177], v103 offset:56336
	ds_read_b128 v[222:225], v103 offset:56352
	ds_read_b128 v[192:195], v103 offset:56368
	s_waitcnt lgkmcnt(11)
	v_fmac_f32_e32 v65, v72, v144
	v_fmac_f32_e32 v64, v72, v145
	v_fmac_f32_e32 v62, v72, v146
	v_fmac_f32_e32 v59, v72, v147
	s_waitcnt lgkmcnt(10)
	v_fmac_f32_e32 v58, v72, v140
	v_fmac_f32_e32 v56, v72, v141
	v_fmac_f32_e32 v54, v72, v142
	v_fmac_f32_e32 v51, v72, v143
	s_waitcnt lgkmcnt(9)
	v_fmac_f32_e32 v67, v72, v148
	v_fmac_f32_e32 v66, v72, v149
	v_fmac_f32_e32 v63, v72, v150
	v_fmac_f32_e32 v61, v72, v151
	s_waitcnt lgkmcnt(8)
	v_fmac_f32_e32 v60, v72, v156
	v_fmac_f32_e32 v57, v72, v157
	v_fmac_f32_e32 v55, v72, v158
	v_fmac_f32_e32 v48, v72, v159
	ds_read_b128 v[226:229], v112
	ds_read_b128 v[196:199], v113
	ds_read_b128 v[230:233], v114
	ds_read_b128 v[234:237], v115
	s_waitcnt lgkmcnt(11)
	v_fmac_f32_e32 v65, v73, v152
	v_fmac_f32_e32 v64, v73, v153
	v_fmac_f32_e32 v62, v73, v154
	v_fmac_f32_e32 v59, v73, v155
	s_waitcnt lgkmcnt(10)
	v_fmac_f32_e32 v58, v73, v170
	v_fmac_f32_e32 v56, v73, v171
	v_fmac_f32_e32 v54, v73, v172
	v_fmac_f32_e32 v51, v73, v173
	s_waitcnt lgkmcnt(7)
	v_fmac_f32_e32 v65, v34, v178
	v_fmac_f32_e32 v64, v34, v179
	v_fmac_f32_e32 v62, v34, v180
	v_fmac_f32_e32 v59, v34, v181
	v_fmac_f32_e32 v67, v73, v188
	v_fmac_f32_e32 v66, v73, v189
	v_fmac_f32_e32 v63, v73, v190
	v_fmac_f32_e32 v61, v73, v191
	s_waitcnt lgkmcnt(6)
	v_fmac_f32_e32 v58, v34, v174
	v_fmac_f32_e32 v56, v34, v175
	v_fmac_f32_e32 v54, v34, v176
	v_fmac_f32_e32 v51, v34, v177
	v_fmac_f32_e32 v60, v73, v182
	v_fmac_f32_e32 v57, v73, v183
	v_fmac_f32_e32 v55, v73, v184
	v_fmac_f32_e32 v48, v73, v185
	s_waitcnt lgkmcnt(5)
	v_fmac_f32_e32 v67, v34, v222
	v_fmac_f32_e32 v66, v34, v223
	v_fmac_f32_e32 v63, v34, v224
	v_fmac_f32_e32 v61, v34, v225
	s_waitcnt lgkmcnt(4)
	v_fmac_f32_e32 v60, v34, v192
	v_fmac_f32_e32 v57, v34, v193
	v_fmac_f32_e32 v55, v34, v194
	v_fmac_f32_e32 v48, v34, v195
	s_waitcnt lgkmcnt(3)
	v_fmac_f32_e32 v65, v35, v226
	v_fmac_f32_e32 v64, v35, v227
	v_fmac_f32_e32 v62, v35, v228
	v_fmac_f32_e32 v59, v35, v229
	s_waitcnt lgkmcnt(2)
	v_fmac_f32_e32 v58, v35, v196
	v_fmac_f32_e32 v56, v35, v197
	v_fmac_f32_e32 v54, v35, v198
	v_fmac_f32_e32 v51, v35, v199
	s_waitcnt lgkmcnt(1)
	v_fmac_f32_e32 v67, v35, v230
	v_fmac_f32_e32 v66, v35, v231
	v_fmac_f32_e32 v63, v35, v232
	v_fmac_f32_e32 v61, v35, v233
	s_waitcnt lgkmcnt(0)
	v_fmac_f32_e32 v60, v35, v234
	v_fmac_f32_e32 v57, v35, v235
	v_fmac_f32_e32 v55, v35, v236
	v_fmac_f32_e32 v48, v35, v237
	v_cndmask_b32_e32 v140, v65, v67, vcc
	v_cndmask_b32_e32 v141, v67, v65, vcc
	v_cndmask_b32_e32 v142, v64, v66, vcc
	v_cndmask_b32_e32 v143, v66, v64, vcc
	v_cndmask_b32_e32 v144, v63, v62, vcc
	v_cndmask_b32_e32 v145, v61, v59, vcc
	v_cndmask_b32_e32 v146, v60, v58, vcc
	v_cndmask_b32_e32 v147, v62, v63, vcc
	v_cndmask_b32_e32 v148, v57, v56, vcc
	v_cndmask_b32_e32 v149, v55, v54, vcc
	v_cndmask_b32_e32 v150, v48, v51, vcc
	v_cndmask_b32_e32 v151, v59, v61, vcc
	v_cndmask_b32_e32 v152, v58, v60, vcc
	v_cndmask_b32_e32 v153, v56, v57, vcc
	v_cndmask_b32_e32 v154, v54, v55, vcc
	v_cndmask_b32_e32 v155, v51, v48, vcc
	ds_bpermute_b32 v156, v96, v140
	ds_bpermute_b32 v157, v96, v142
	ds_bpermute_b32 v158, v96, v147
	ds_bpermute_b32 v159, v96, v151
	ds_bpermute_b32 v170, v96, v152
	ds_bpermute_b32 v171, v96, v153
	ds_bpermute_b32 v172, v96, v154
	ds_bpermute_b32 v173, v96, v155
	s_waitcnt lgkmcnt(7)
	v_add_f32_e32 v174, v141, v156
	s_waitcnt lgkmcnt(6)
	v_add_f32_e32 v175, v143, v157
	s_waitcnt lgkmcnt(5)
	v_add_f32_e32 v176, v144, v158
	s_waitcnt lgkmcnt(4)
	v_add_f32_e32 v177, v145, v159
	s_waitcnt lgkmcnt(3)
	v_add_f32_e32 v178, v146, v170
	s_waitcnt lgkmcnt(2)
	v_add_f32_e32 v39, v148, v171
	s_waitcnt lgkmcnt(1)
	v_add_f32_e32 v40, v149, v172
	s_waitcnt lgkmcnt(0)
	v_add_f32_e32 v41, v150, v173
	v_cndmask_b32_e64 v42, v174, v178, s[42:43]
	v_cndmask_b32_e64 v179, v178, v174, s[42:43]
	v_cndmask_b32_e64 v180, v175, v39, s[42:43]
	v_cndmask_b32_e64 v181, v39, v175, s[42:43]
	v_cndmask_b32_e64 v182, v176, v40, s[42:43]
	v_cndmask_b32_e64 v183, v40, v176, s[42:43]
	v_cndmask_b32_e64 v184, v177, v41, s[42:43]
	v_cndmask_b32_e64 v185, v41, v177, s[42:43]
	ds_bpermute_b32 v188, v97, v42
	ds_bpermute_b32 v189, v97, v180
	ds_bpermute_b32 v190, v97, v182
	ds_bpermute_b32 v191, v97, v184
	s_waitcnt lgkmcnt(3)
	v_add_f32_e32 v192, v179, v188
	s_waitcnt lgkmcnt(2)
	v_add_f32_e32 v193, v181, v189
	s_waitcnt lgkmcnt(1)
	v_add_f32_e32 v194, v183, v190
	s_waitcnt lgkmcnt(0)
	v_add_f32_e32 v37, v185, v191
	v_cndmask_b32_e64 v38, v192, v194, s[44:45]
	v_cndmask_b32_e64 v195, v194, v192, s[44:45]
	v_cndmask_b32_e64 v196, v193, v37, s[44:45]
	v_cndmask_b32_e64 v197, v37, v193, s[44:45]
	ds_bpermute_b32 v198, v98, v38
	ds_bpermute_b32 v199, v98, v196
	s_waitcnt lgkmcnt(1)
	v_add_f32_e32 v222, v195, v198
	s_waitcnt lgkmcnt(0)
	v_add_f32_e32 v223, v197, v199
	v_cndmask_b32_e64 v36, v222, v223, s[46:47]
	v_cndmask_b32_e64 v224, v223, v222, s[46:47]
	ds_bpermute_b32 v225, v99, v36
	s_waitcnt lgkmcnt(0)
	v_add_f32_e32 v226, v224, v225
	ds_bpermute_b32 v227, v100, v226
	s_waitcnt lgkmcnt(0)
	v_add_f32_e32 v34, v226, v227
	ds_bpermute_b32 v35, v101, v34
	s_and_b64 exec, exec, s[48:49]
	s_cbranch_execz .LBB0_1060
; __device__ __forceinline__ float logsigmoidf_(float x) { return fminf(x, 0.0f) - log1pf(__expf(-fabsf(x))); }
; __device__ void phase0(const Params& P, LAS unsigned char* lds, const int G, const int bid) {
;     ...
;               r1 += __shfl_xor(r1, 2); r1 += __shfl_xor(r1, 1);
;               if ((lane & 3) == 0) { float gv = r1 + gbias; if (gcol >= 8) gv = logsigmoidf_(gv); gates[(size_t)row * 16 + gcol] = gv; }
	s_waitcnt lgkmcnt(0)
	v_add_f32_e32 v34, v34, v35
	v_add_f32_e32 v34, v91, v34
	s_and_saveexec_b64 s[8:9], s[40:41]
	s_cbranch_execz .LBB0_1059
	s_mov_b32 s12, 0xbfb8aa3b
	v_mul_f32_e64 v35, |v34|, s12
	v_exp_f32_e32 v48, v35
	v_max_f32_e32 v34, v34, v34
	v_min_f32_e32 v49, 0, v34
	s_mov_b32 s12, 0x3f2aaaab
	v_add_f32_e32 v36, 1.0, v48
	v_add_f32_e32 v34, -1.0, v36
	v_sub_f32_e32 v35, v34, v36
	v_sub_f32_e32 v34, v48, v34
	v_add_f32_e32 v35, 1.0, v35
	v_add_f32_e32 v37, v34, v35
	v_frexp_mant_f32_e32 v38, v36
	v_cvt_f64_f32_e32 v[34:35], v36
	v_frexp_exp_i32_f64_e32 v34, v[34:35]
	v_cmp_gt_f32_e64 s[50:51], s12, v38
	s_mov_b32 s12, 0x3f317218
	s_nop 0
	v_subbrev_co_u32_e64 v42, s[50:51], 0, v34, s[50:51]
	v_sub_u32_e32 v34, 0, v42
	v_ldexp_f32 v35, v36, v34
	v_add_f32_e32 v36, -1.0, v35
	v_add_f32_e32 v38, 1.0, v35
	v_ldexp_f32 v34, v37, v34
	v_add_f32_e32 v37, 1.0, v36
	v_add_f32_e32 v39, -1.0, v38
	v_sub_f32_e32 v37, v35, v37
	v_sub_f32_e32 v35, v35, v39
	v_add_f32_e32 v37, v34, v37
	v_add_f32_e32 v34, v34, v35
	v_add_f32_e32 v43, v38, v34
	v_rcp_f32_e32 v45, v43
	v_sub_f32_e32 v35, v43, v38
	v_sub_f32_e32 v44, v34, v35
	v_add_f32_e32 v35, v36, v37
	v_mul_f32_e32 v47, v35, v45
	v_sub_f32_e32 v34, v35, v36
	v_mul_f32_e32 v36, v43, v47
	v_fma_f32 v38, v47, v43, -v36
	v_fmac_f32_e32 v38, v47, v44
	v_sub_f32_e32 v46, v37, v34
	v_add_f32_e32 v34, v36, v38
	v_sub_f32_e32 v37, v35, v34
	v_pk_add_f32 v[40:41], v[34:35], v[36:37] neg_lo:[0,1] neg_hi:[0,1]
	v_mov_b32_e32 v39, v34
	v_pk_add_f32 v[34:35], v[40:41], v[38:39] neg_lo:[0,1] neg_hi:[0,1]
	s_nop 0
	v_add_f32_e32 v35, v46, v35
	v_add_f32_e32 v34, v34, v35
	v_add_f32_e32 v35, v37, v34
	v_mul_f32_e32 v46, v45, v35
	v_mul_f32_e32 v36, v43, v46
	v_fma_f32 v38, v46, v43, -v36
	v_fmac_f32_e32 v38, v46, v44
	v_sub_f32_e32 v37, v37, v35
	v_add_f32_e32 v43, v34, v37
	v_add_f32_e32 v34, v36, v38
	v_sub_f32_e32 v37, v35, v34
	v_pk_add_f32 v[40:41], v[34:35], v[36:37] neg_lo:[0,1] neg_hi:[0,1]
	v_mov_b32_e32 v39, v34
	v_pk_add_f32 v[34:35], v[40:41], v[38:39] neg_lo:[0,1] neg_hi:[0,1]
	s_nop 0
	v_add_f32_e32 v35, v43, v35
	v_add_f32_e32 v34, v34, v35
	v_add_f32_e32 v35, v47, v46
	v_add_f32_e32 v34, v37, v34
	v_sub_f32_e32 v36, v35, v47
	v_mul_f32_e32 v34, v45, v34
	v_sub_f32_e32 v36, v46, v36
	v_add_f32_e32 v36, v36, v34
	v_add_f32_e32 v38, v35, v36
	v_mul_f32_e32 v39, v38, v38
	v_fmamk_f32 v34, v39, 0x3e9b6dac, v208
	v_fmaak_f32 v169, v39, v34, 0x3f2aaada
	v_cvt_f32_i32_e32 v34, v42
	v_sub_f32_e32 v35, v38, v35
	v_sub_f32_e32 v35, v36, v35
	v_ldexp_f32 v40, v35, 1
	v_mul_f32_e32 v35, v38, v39
	v_ldexp_f32 v37, v38, 1
	v_pk_mul_f32 v[38:39], v[34:35], v[168:169]
	s_nop 0
	v_fma_f32 v36, v34, s12, -v38
	v_fmac_f32_e32 v36, 0xb102e308, v34
	v_pk_add_f32 v[34:35], v[38:39], v[36:37]
	s_mov_b32 s12, 0x7f800000
	v_sub_f32_e32 v37, v35, v37
	v_sub_f32_e32 v37, v39, v37
	v_add_f32_e32 v41, v40, v37
	v_mov_b32_e32 v40, v38
	v_pk_add_f32 v[38:39], v[34:35], v[38:39] neg_lo:[0,1] neg_hi:[0,1]
	v_pk_add_f32 v[42:43], v[34:35], v[40:41]
	v_mov_b32_e32 v37, v34
	v_mov_b32_e32 v39, v43
	v_pk_add_f32 v[44:45], v[36:37], v[38:39] neg_lo:[0,1] neg_hi:[0,1]
	v_pk_add_f32 v[36:37], v[36:37], v[38:39]
	v_mov_b32_e32 v40, v41
	v_pk_add_f32 v[38:39], v[36:37], v[34:35] op_sel:[1,0] op_sel_hi:[0,1] neg_lo:[0,1] neg_hi:[0,1]
	s_nop 0
	v_pk_add_f32 v[46:47], v[42:43], v[38:39] op_sel_hi:[1,0] neg_lo:[0,1] neg_hi:[0,1]
	v_mov_b32_e32 v42, v43
	v_mov_b32_e32 v43, v37
	v_pk_mov_b32 v[38:39], v[34:35], v[38:39] op_sel:[1,0]
	v_mov_b32_e32 v41, v34
	v_pk_add_f32 v[38:39], v[42:43], v[38:39] neg_lo:[0,1] neg_hi:[0,1]
	v_mov_b32_e32 v46, v44
	v_pk_add_f32 v[34:35], v[40:41], v[38:39] neg_lo:[0,1] neg_hi:[0,1]
	v_mov_b32_e32 v45, v37
	v_pk_add_f32 v[38:39], v[46:47], v[34:35]
	v_cmp_neq_f32_e64 s[50:51], s12, v48
	v_pk_add_f32 v[40:41], v[38:39], v[38:39] op_sel:[0,1] op_sel_hi:[1,0]
	s_mov_b32 s12, 0x33800000
	v_pk_add_f32 v[36:37], v[36:37], v[40:41] op_sel:[1,0] op_sel_hi:[0,1]
	s_nop 0
	v_mov_b32_e32 v39, v36
	v_pk_add_f32 v[42:43], v[38:39], v[44:45] neg_lo:[0,1] neg_hi:[0,1]
	v_mov_b32_e32 v35, v40
	v_sub_f32_e32 v37, v38, v42
	v_pk_add_f32 v[34:35], v[34:35], v[42:43] neg_lo:[0,1] neg_hi:[0,1]
	v_sub_f32_e32 v37, v44, v37
	v_add_f32_e32 v34, v34, v37
	v_add_f32_e32 v34, v34, v35
	v_add_f32_e32 v34, v36, v34
	v_cndmask_b32_e64 v34, v212, v34, s[50:51]
	v_cmp_ngt_f32_e64 s[50:51], -1.0, v48
	s_nop 1
	v_cndmask_b32_e64 v34, v213, v34, s[50:51]
	v_cmp_neq_f32_e64 s[50:51], -1.0, v48
	s_nop 1
	v_cndmask_b32_e64 v34, v214, v34, s[50:51]
	v_cmp_lt_f32_e64 s[50:51], |v48|, s12
	s_nop 1
	v_cndmask_b32_e64 v34, v34, v48, s[50:51]
	v_sub_f32_e32 v34, v49, v34

; #define LAS __attribute__((address_space(3)))
; __device__ __forceinline__ unsigned cvt_pk_bf16(float lo, float hi) { unsigned r; asm volatile("v_cvt_pk_bf16_f32 %0, %1, %2" : "=v"(r) : "v"(lo), "v"(hi)); return r; }
; __device__ void phase0(const Params& P, LAS unsigned char* lds, const int G, const int bid) {
;     ...
;           for (int rr = 0; rr < 4; ++rr) { const int row = row0 + rr * G * 8; if (row >= NTOK) continue;
;               f32x4 (&v)[4] = vv[rr]; float ss = 0.f;
; #pragma unroll
;               for (int i = 0; i < 4; ++i)
; #pragma unroll
;                   for (int j = 0; j < 4; ++j) ss += v[i][j] * v[i][j];
; #pragma unroll
;               for (int o = 32; o >= 1; o >>= 1) ss += __shfl_xor(ss, o);
;               const float rstd = rsqrtf(ss * (1.0f / DM) + 1e-6f);
;               float ga[16];
; #pragma unroll
;               for (int c = 0; c < 16; ++c) ga[c] = 0.f;
; #pragma unroll
;               for (int i = 0; i < 4; ++i) { v[i] = v[i] * rstd * w4[i];
;                   u32x2 w; w.x = cvt_pk_bf16(v[i][0], v[i][1]); w.y = cvt_pk_bf16(v[i][2], v[i][3]);
;                   *(u32x2*)(abf + (size_t)row * DM + 4 * lane + 256 * i) = w;
; #pragma unroll
;                   for (int j = 0; j < 4; ++j) { const LAS float* wr_ = wg + (j * 256 + i * 64 + lane) * 20; const float a = v[i][j];
; #pragma unroll
;                       for (int q = 0; q < 4; ++q) { const f32x4 wv = *(const LAS f32x4*)(wr_ + 4 * q);
;                           ga[4 * q] += a * wv[0]; ga[4 * q + 1] += a * wv[1]; ga[4 * q + 2] += a * wv[2]; ga[4 * q + 3] += a * wv[3]; } } }
.LBB0_1060:
	s_or_b64 exec, exec, s[6:7]
	v_cmp_gt_i32_e64 s[50:51], s15, v84
	s_and_saveexec_b64 s[6:7], s[50:51]
	s_cbranch_execz .LBB0_1045
	s_waitcnt vmcnt(7)
	v_mul_f32_e32 v38, v31, v31
	v_fmac_f32_e32 v38, v30, v30
	v_fmac_f32_e32 v38, v32, v32
	v_fmac_f32_e32 v38, v33, v33
	s_waitcnt vmcnt(6)
	v_fmac_f32_e32 v38, v26, v26
	v_fmac_f32_e32 v38, v27, v27
	v_fmac_f32_e32 v38, v28, v28
	v_fmac_f32_e32 v38, v29, v29
	s_waitcnt vmcnt(5)
	v_fmac_f32_e32 v38, v22, v22
	v_fmac_f32_e32 v38, v23, v23
	v_fmac_f32_e32 v38, v24, v24
	v_fmac_f32_e32 v38, v25, v25
	s_waitcnt vmcnt(4)
	v_pk_mul_f32 v[36:37], v[18:19], v[18:19]
	s_waitcnt lgkmcnt(0)
	v_pk_mul_f32 v[34:35], v[20:21], v[20:21]
	v_add_f32_e32 v36, v36, v38
	v_add_f32_e32 v36, v37, v36
	v_add_f32_e32 v34, v34, v36
	v_add_f32_e32 v34, v35, v34
	ds_bpermute_b32 v35, v96, v34
	v_ashrrev_i32_e32 v85, 31, v84
	v_lshlrev_b64 v[36:37], 11, v[84:85]
	v_lshl_add_u64 v[36:37], v[80:81], 0, v[36:37]
	s_waitcnt lgkmcnt(0)
	v_add_f32_e32 v34, v34, v35
	ds_bpermute_b32 v35, v97, v34
	s_waitcnt lgkmcnt(0)
	v_add_f32_e32 v34, v34, v35
	ds_bpermute_b32 v35, v98, v34
	s_waitcnt lgkmcnt(0)
	v_add_f32_e32 v34, v34, v35
	ds_bpermute_b32 v35, v99, v34
	s_waitcnt lgkmcnt(0)
	v_add_f32_e32 v34, v34, v35
	ds_bpermute_b32 v35, v100, v34
	s_waitcnt lgkmcnt(0)
	v_add_f32_e32 v34, v34, v35
	ds_bpermute_b32 v35, v101, v34
	s_waitcnt lgkmcnt(0)
	v_add_f32_e32 v34, v34, v35
	v_fmamk_f32 v34, v34, 0x3a800000, v210
	v_cmp_gt_f32_e64 s[50:51], s30, v34
	v_mul_f32_e32 v35, 0x4b800000, v34
	s_nop 0
	v_cndmask_b32_e64 v34, v34, v35, s[50:51]
	v_rsq_f32_e32 v34, v34
	s_nop 0
	v_mul_f32_e32 v35, 0x45800000, v34
	v_cndmask_b32_e64 v34, v34, v35, s[50:51]
	v_pk_mul_f32 v[38:39], v[30:31], v[34:35] op_sel_hi:[1,0]
	v_pk_mul_f32 v[30:31], v[32:33], v[34:35] op_sel_hi:[1,0]
	v_pk_mul_f32 v[32:33], v[2:3], v[38:39]
	v_pk_mul_f32 v[30:31], v[4:5], v[30:31]
	v_cvt_pk_bf16_f32 v38, v32, v33
	s_nop 0
	v_cvt_pk_bf16_f32 v39, v30, v31
	global_store_dwordx2 v[36:37], v[38:39], off
	ds_read_b128 v[140:143], v102 offset:40960
	ds_read_b128 v[144:147], v102 offset:40976
	ds_read_b128 v[148:151], v102 offset:40992
	ds_read_b128 v[152:155], v102 offset:41008
	ds_read_b128 v[156:159], v102 offset:61440
	ds_read_b128 v[170:173], v102 offset:61456
	ds_read_b128 v[174:177], v102 offset:61472
	ds_read_b128 v[178:181], v102 offset:61488
	ds_read_b128 v[182:185], v103 offset:40960
	ds_read_b128 v[188:191], v103 offset:40976
	ds_read_b128 v[192:195], v103 offset:40992
	ds_read_b128 v[196:199], v103 offset:41008
	s_waitcnt lgkmcnt(11)
	v_fma_f32 v49, v140, v32, 0
	v_fma_f32 v46, v142, v32, 0
	s_waitcnt lgkmcnt(10)
	v_fma_f32 v42, v144, v32, 0
	v_fma_f32 v40, v145, v32, 0
	v_fma_f32 v38, v146, v32, 0
	v_fma_f32 v35, v147, v32, 0
	s_waitcnt lgkmcnt(9)
	v_fma_f32 v51, v148, v32, 0
	v_fma_f32 v50, v149, v32, 0
	ds_read_b128 v[222:225], v103 offset:61440
	v_fma_f32 v48, v141, v32, 0
	v_fma_f32 v43, v143, v32, 0
	v_fma_f32 v47, v150, v32, 0
	v_fma_f32 v45, v151, v32, 0
	s_waitcnt lgkmcnt(8)
	v_fmac_f32_e32 v49, v156, v33
	v_fmac_f32_e32 v48, v157, v33
	v_fmac_f32_e32 v46, v158, v33
	v_fmac_f32_e32 v43, v159, v33
	ds_read_b128 v[226:229], v103 offset:61456
	v_fma_f32 v44, v152, v32, 0
	v_fma_f32 v41, v153, v32, 0
	v_fma_f32 v39, v154, v32, 0
	v_fma_f32 v32, v155, v32, 0
	s_waitcnt lgkmcnt(8)
	v_fmac_f32_e32 v42, v170, v33
	v_fmac_f32_e32 v40, v171, v33
	v_fmac_f32_e32 v38, v172, v33
	v_fmac_f32_e32 v35, v173, v33
	ds_read_b128 v[230:233], v103 offset:61472
	s_waitcnt lgkmcnt(8)
	v_fmac_f32_e32 v51, v174, v33
	v_fmac_f32_e32 v50, v175, v33
	v_fmac_f32_e32 v47, v176, v33
	v_fmac_f32_e32 v45, v177, v33
	ds_read_b128 v[234:237], v103 offset:61488
	s_waitcnt lgkmcnt(8)
	v_fmac_f32_e32 v44, v178, v33
	v_fmac_f32_e32 v41, v179, v33
	v_fmac_f32_e32 v39, v180, v33
	v_fmac_f32_e32 v32, v181, v33
	ds_read_b128 v[144:147], v102 offset:46080
	ds_read_b128 v[140:143], v102 offset:46096
	ds_read_b128 v[148:151], v102 offset:46112
	ds_read_b128 v[156:159], v102 offset:46128
	s_waitcnt lgkmcnt(11)
	v_fmac_f32_e32 v49, v182, v30
	v_fmac_f32_e32 v48, v183, v30
	v_fmac_f32_e32 v46, v184, v30
	v_fmac_f32_e32 v43, v185, v30
	ds_read_b128 v[152:155], v103 offset:25600
	s_waitcnt lgkmcnt(11)
	v_fmac_f32_e32 v42, v30, v188
	v_fmac_f32_e32 v40, v30, v189
	v_fmac_f32_e32 v38, v30, v190
	v_fmac_f32_e32 v35, v30, v191
	s_waitcnt lgkmcnt(8)
	v_fmac_f32_e32 v49, v31, v222
	v_fmac_f32_e32 v48, v31, v223
	v_fmac_f32_e32 v46, v31, v224
	v_fmac_f32_e32 v43, v31, v225
	ds_read_b128 v[170:173], v103 offset:25616
	v_fmac_f32_e32 v51, v30, v192
	v_fmac_f32_e32 v50, v30, v193
	v_fmac_f32_e32 v47, v30, v194
	v_fmac_f32_e32 v45, v30, v195
	s_waitcnt lgkmcnt(8)
	v_fmac_f32_e32 v42, v31, v226
	v_fmac_f32_e32 v40, v31, v227
	v_fmac_f32_e32 v38, v31, v228
	v_fmac_f32_e32 v35, v31, v229
	ds_read_b128 v[174:177], v103 offset:25632
	v_fmac_f32_e32 v44, v30, v196
	v_fmac_f32_e32 v41, v30, v197
	v_fmac_f32_e32 v39, v30, v198
	v_fmac_f32_e32 v32, v30, v199
	s_waitcnt lgkmcnt(8)
	v_fmac_f32_e32 v51, v31, v230
	v_fmac_f32_e32 v50, v31, v231
	v_fmac_f32_e32 v47, v31, v232
	v_fmac_f32_e32 v45, v31, v233
	ds_read_b128 v[178:181], v103 offset:25648
	s_waitcnt lgkmcnt(8)
	v_fmac_f32_e32 v44, v31, v234
	v_fmac_f32_e32 v41, v31, v235
	v_fmac_f32_e32 v39, v31, v236
	v_fmac_f32_e32 v32, v31, v237
	v_pk_mul_f32 v[30:31], v[26:27], v[34:35] op_sel_hi:[1,0]
	v_pk_mul_f32 v[26:27], v[28:29], v[34:35] op_sel_hi:[1,0]
	v_pk_mul_f32 v[64:65], v[6:7], v[30:31]
	v_pk_mul_f32 v[26:27], v[8:9], v[26:27]
	v_cvt_pk_bf16_f32 v28, v64, v65
	s_nop 0
	v_cvt_pk_bf16_f32 v29, v26, v27
	global_store_dwordx2 v[36:37], v[28:29], off offset:512
	ds_read_b128 v[182:185], v103 offset:46080
	ds_read_b128 v[188:191], v103 offset:46096
	ds_read_b128 v[222:225], v103 offset:46112
	ds_read_b128 v[192:195], v103 offset:46128
	s_waitcnt lgkmcnt(11)
; #define LAS __attribute__((address_space(3)))
; __device__ __forceinline__ unsigned cvt_pk_bf16(float lo, float hi) { unsigned r; asm volatile("v_cvt_pk_bf16_f32 %0, %1, %2" : "=v"(r) : "v"(lo), "v"(hi)); return r; }
; __device__ void phase0(const Params& P, LAS unsigned char* lds, const int G, const int bid) {
;     ...
;               for (int i = 0; i < 4; ++i) { v[i] = v[i] * rstd * w4[i];
;                   u32x2 w; w.x = cvt_pk_bf16(v[i][0], v[i][1]); w.y = cvt_pk_bf16(v[i][2], v[i][3]);
;                   *(u32x2*)(abf + (size_t)row * DM + 4 * lane + 256 * i) = w;
; #pragma unroll
;                   for (int j = 0; j < 4; ++j) { const LAS float* wr_ = wg + (j * 256 + i * 64 + lane) * 20; const float a = v[i][j];
; #pragma unroll
;                       for (int q = 0; q < 4; ++q) { const f32x4 wv = *(const LAS f32x4*)(wr_ + 4 * q);
;                           ga[4 * q] += a * wv[0]; ga[4 * q + 1] += a * wv[1]; ga[4 * q + 2] += a * wv[2]; ga[4 * q + 3] += a * wv[3]; } } }
	v_fmac_f32_e32 v49, v64, v144
	v_fmac_f32_e32 v48, v64, v145
	v_fmac_f32_e32 v46, v64, v146
	v_fmac_f32_e32 v43, v64, v147
	s_waitcnt lgkmcnt(10)
	v_fmac_f32_e32 v42, v64, v140
	v_fmac_f32_e32 v40, v64, v141
	v_fmac_f32_e32 v38, v64, v142
	v_fmac_f32_e32 v35, v64, v143
	s_waitcnt lgkmcnt(9)
	v_fmac_f32_e32 v51, v64, v148
	v_fmac_f32_e32 v50, v64, v149
	v_fmac_f32_e32 v47, v64, v150
	v_fmac_f32_e32 v45, v64, v151
	s_waitcnt lgkmcnt(8)
	v_fmac_f32_e32 v44, v64, v156
	v_fmac_f32_e32 v41, v64, v157
	v_fmac_f32_e32 v39, v64, v158
	v_fmac_f32_e32 v32, v64, v159
	ds_read_b128 v[226:229], v104
	ds_read_b128 v[196:199], v105
	ds_read_b128 v[230:233], v106
	ds_read_b128 v[234:237], v107
	s_waitcnt lgkmcnt(11)
	v_fmac_f32_e32 v49, v65, v152
	v_fmac_f32_e32 v48, v65, v153
	v_fmac_f32_e32 v46, v65, v154
	v_fmac_f32_e32 v43, v65, v155
	ds_read_b128 v[144:147], v102 offset:51200
	s_waitcnt lgkmcnt(11)
	v_fmac_f32_e32 v42, v65, v170
	v_fmac_f32_e32 v40, v65, v171
	v_fmac_f32_e32 v38, v65, v172
	v_fmac_f32_e32 v35, v65, v173
	s_waitcnt lgkmcnt(8)
	v_fmac_f32_e32 v49, v26, v182
	v_fmac_f32_e32 v48, v26, v183
	v_fmac_f32_e32 v46, v26, v184
	v_fmac_f32_e32 v43, v26, v185
	ds_read_b128 v[140:143], v102 offset:51216
	v_fmac_f32_e32 v51, v65, v174
	v_fmac_f32_e32 v50, v65, v175
	v_fmac_f32_e32 v47, v65, v176
	v_fmac_f32_e32 v45, v65, v177
	s_waitcnt lgkmcnt(8)
	v_fmac_f32_e32 v42, v26, v188
	v_fmac_f32_e32 v40, v26, v189
	v_fmac_f32_e32 v38, v26, v190
	v_fmac_f32_e32 v35, v26, v191
	ds_read_b128 v[148:151], v102 offset:51232
	v_fmac_f32_e32 v44, v65, v178
	v_fmac_f32_e32 v41, v65, v179
	v_fmac_f32_e32 v39, v65, v180
	v_fmac_f32_e32 v32, v65, v181
	s_waitcnt lgkmcnt(8)
	v_fmac_f32_e32 v51, v26, v222
	v_fmac_f32_e32 v50, v26, v223
	v_fmac_f32_e32 v47, v26, v224
	v_fmac_f32_e32 v45, v26, v225
	ds_read_b128 v[156:159], v102 offset:51248
	s_waitcnt lgkmcnt(8)
	v_fmac_f32_e32 v44, v26, v192
	v_fmac_f32_e32 v41, v26, v193
	v_fmac_f32_e32 v39, v26, v194
	v_fmac_f32_e32 v32, v26, v195
	ds_read_b128 v[152:155], v103 offset:30720
	s_waitcnt lgkmcnt(8)
	v_fmac_f32_e32 v49, v27, v226
	v_fmac_f32_e32 v48, v27, v227
	v_fmac_f32_e32 v46, v27, v228
	v_fmac_f32_e32 v43, v27, v229
	ds_read_b128 v[170:173], v103 offset:30736
	s_waitcnt lgkmcnt(8)
	v_fmac_f32_e32 v42, v27, v196
	v_fmac_f32_e32 v40, v27, v197
	v_fmac_f32_e32 v38, v27, v198
	v_fmac_f32_e32 v35, v27, v199
	ds_read_b128 v[182:185], v103 offset:30752
	s_waitcnt lgkmcnt(8)
	v_fmac_f32_e32 v51, v27, v230
	v_fmac_f32_e32 v50, v27, v231
	v_fmac_f32_e32 v47, v27, v232
	v_fmac_f32_e32 v45, v27, v233
	ds_read_b128 v[174:177], v103 offset:30768
	s_waitcnt lgkmcnt(8)
	v_fmac_f32_e32 v44, v27, v234
	v_fmac_f32_e32 v41, v27, v235
	v_fmac_f32_e32 v39, v27, v236
	v_fmac_f32_e32 v32, v27, v237
	v_pk_mul_f32 v[26:27], v[22:23], v[34:35] op_sel_hi:[1,0]
	v_pk_mul_f32 v[22:23], v[24:25], v[34:35] op_sel_hi:[1,0]
	v_pk_mul_f32 v[60:61], v[10:11], v[26:27]
	v_pk_mul_f32 v[22:23], v[12:13], v[22:23]
	v_cvt_pk_bf16_f32 v24, v60, v61
	s_nop 0
	v_cvt_pk_bf16_f32 v25, v22, v23
	global_store_dwordx2 v[36:37], v[24:25], off offset:1024
	ds_read_b128 v[188:191], v103 offset:51200
	ds_read_b128 v[178:181], v103 offset:51216
	ds_read_b128 v[222:225], v103 offset:51232
	ds_read_b128 v[192:195], v103 offset:51248
	s_waitcnt lgkmcnt(11)
	v_fmac_f32_e32 v49, v60, v144
	v_fmac_f32_e32 v48, v60, v145
	v_fmac_f32_e32 v46, v60, v146
	v_fmac_f32_e32 v43, v60, v147
	s_waitcnt lgkmcnt(10)
	v_fmac_f32_e32 v42, v60, v140
	v_fmac_f32_e32 v40, v60, v141
	v_fmac_f32_e32 v38, v60, v142
	v_fmac_f32_e32 v35, v60, v143
	s_waitcnt lgkmcnt(9)
	v_fmac_f32_e32 v51, v60, v148
	v_fmac_f32_e32 v50, v60, v149
	v_fmac_f32_e32 v47, v60, v150
	v_fmac_f32_e32 v45, v60, v151
	s_waitcnt lgkmcnt(8)
	v_fmac_f32_e32 v44, v60, v156
	v_fmac_f32_e32 v41, v60, v157
	v_fmac_f32_e32 v39, v60, v158
	v_fmac_f32_e32 v32, v60, v159
	ds_read_b128 v[226:229], v108
	ds_read_b128 v[196:199], v109
	ds_read_b128 v[230:233], v110
	ds_read_b128 v[234:237], v111
	s_waitcnt lgkmcnt(11)
	v_fmac_f32_e32 v49, v61, v152
	v_fmac_f32_e32 v48, v61, v153
	v_fmac_f32_e32 v46, v61, v154
	v_fmac_f32_e32 v43, v61, v155
	ds_read_b128 v[144:147], v102 offset:56320
	s_waitcnt lgkmcnt(11)
	v_fmac_f32_e32 v42, v61, v170
	v_fmac_f32_e32 v40, v61, v171
	v_fmac_f32_e32 v38, v61, v172
	v_fmac_f32_e32 v35, v61, v173
	s_waitcnt lgkmcnt(8)
	v_fmac_f32_e32 v49, v22, v188
	v_fmac_f32_e32 v48, v22, v189
	v_fmac_f32_e32 v46, v22, v190
	v_fmac_f32_e32 v43, v22, v191
	ds_read_b128 v[140:143], v102 offset:56336
	v_fmac_f32_e32 v51, v61, v182
	v_fmac_f32_e32 v50, v61, v183
	v_fmac_f32_e32 v47, v61, v184
	v_fmac_f32_e32 v45, v61, v185
	s_waitcnt lgkmcnt(8)
	v_fmac_f32_e32 v42, v22, v178
	v_fmac_f32_e32 v40, v22, v179
	v_fmac_f32_e32 v38, v22, v180
	v_fmac_f32_e32 v35, v22, v181
	ds_read_b128 v[148:151], v102 offset:56352
	v_fmac_f32_e32 v44, v61, v174
	v_fmac_f32_e32 v41, v61, v175
	v_fmac_f32_e32 v39, v61, v176
	v_fmac_f32_e32 v32, v61, v177
	s_waitcnt lgkmcnt(8)
	v_fmac_f32_e32 v51, v22, v222
	v_fmac_f32_e32 v50, v22, v223
	v_fmac_f32_e32 v47, v22, v224
	v_fmac_f32_e32 v45, v22, v225
	ds_read_b128 v[156:159], v102 offset:56368
	s_waitcnt lgkmcnt(8)
	v_fmac_f32_e32 v44, v22, v192
	v_fmac_f32_e32 v41, v22, v193
	v_fmac_f32_e32 v39, v22, v194
	v_fmac_f32_e32 v32, v22, v195
	ds_read_b128 v[152:155], v103 offset:35840
	s_waitcnt lgkmcnt(8)
	v_fmac_f32_e32 v49, v23, v226
	v_fmac_f32_e32 v48, v23, v227
	v_fmac_f32_e32 v46, v23, v228
	v_fmac_f32_e32 v43, v23, v229
	ds_read_b128 v[170:173], v103 offset:35856
	s_waitcnt lgkmcnt(8)
	v_fmac_f32_e32 v42, v23, v196
	v_fmac_f32_e32 v40, v23, v197
	v_fmac_f32_e32 v38, v23, v198
	v_fmac_f32_e32 v35, v23, v199
	ds_read_b128 v[188:191], v103 offset:35872
	s_waitcnt lgkmcnt(8)
; #define LAS __attribute__((address_space(3)))
; __device__ __forceinline__ unsigned cvt_pk_bf16(float lo, float hi) { unsigned r; asm volatile("v_cvt_pk_bf16_f32 %0, %1, %2" : "=v"(r) : "v"(lo), "v"(hi)); return r; }
; __device__ void phase0(const Params& P, LAS unsigned char* lds, const int G, const int bid) {
;     ...
;               for (int i = 0; i < 4; ++i) { v[i] = v[i] * rstd * w4[i];
;                   u32x2 w; w.x = cvt_pk_bf16(v[i][0], v[i][1]); w.y = cvt_pk_bf16(v[i][2], v[i][3]);
;                   *(u32x2*)(abf + (size_t)row * DM + 4 * lane + 256 * i) = w;
; #pragma unroll
;                   for (int j = 0; j < 4; ++j) { const LAS float* wr_ = wg + (j * 256 + i * 64 + lane) * 20; const float a = v[i][j];
; #pragma unroll
;                       for (int q = 0; q < 4; ++q) { const f32x4 wv = *(const LAS f32x4*)(wr_ + 4 * q);
;                           ga[4 * q] += a * wv[0]; ga[4 * q + 1] += a * wv[1]; ga[4 * q + 2] += a * wv[2]; ga[4 * q + 3] += a * wv[3]; } } }
;               float r8[8], r4[4], r2[2], r1;
; #pragma unroll
;               for (int c = 0; c < 8; ++c) { const bool hi = (lane & 32) != 0; const float send = hi ? ga[c] : ga[c + 8], keep = hi ? ga[c + 8] : ga[c]; r8[c] = keep + __shfl_xor(send, 32); }
; #pragma unroll
;               for (int c = 0; c < 4; ++c) { const bool hi = (lane & 16) != 0; const float send = hi ? r8[c] : r8[c + 4], keep = hi ? r8[c + 4] : r8[c]; r4[c] = keep + __shfl_xor(send, 16); }
; #pragma unroll
;               for (int c = 0; c < 2; ++c) { const bool hi = (lane & 8) != 0; const float send = hi ? r4[c] : r4[c + 2], keep = hi ? r4[c + 2] : r4[c]; r2[c] = keep + __shfl_xor(send, 8); }
;               { const bool hi = (lane & 4) != 0; const float send = hi ? r2[0] : r2[1], keep = hi ? r2[1] : r2[0]; r1 = keep + __shfl_xor(send, 4); }
;               r1 += __shfl_xor(r1, 2); r1 += __shfl_xor(r1, 1);
	v_fmac_f32_e32 v51, v23, v230
	v_fmac_f32_e32 v50, v23, v231
	v_fmac_f32_e32 v47, v23, v232
	v_fmac_f32_e32 v45, v23, v233
	ds_read_b128 v[182:185], v103 offset:35888
	s_waitcnt lgkmcnt(8)
	v_fmac_f32_e32 v44, v23, v234
	v_fmac_f32_e32 v41, v23, v235
	v_fmac_f32_e32 v39, v23, v236
	v_fmac_f32_e32 v32, v23, v237
	v_pk_mul_f32 v[22:23], v[18:19], v[34:35] op_sel_hi:[1,0]
	v_pk_mul_f32 v[18:19], v[20:21], v[34:35] op_sel_hi:[1,0]
	v_pk_mul_f32 v[56:57], v[14:15], v[22:23]
	v_pk_mul_f32 v[18:19], v[16:17], v[18:19]
	v_cvt_pk_bf16_f32 v20, v56, v57
	s_nop 0
	v_cvt_pk_bf16_f32 v21, v18, v19
	global_store_dwordx2 v[36:37], v[20:21], off offset:1536
	ds_read_b128 v[178:181], v103 offset:56320
	ds_read_b128 v[174:177], v103 offset:56336
	ds_read_b128 v[222:225], v103 offset:56352
	ds_read_b128 v[192:195], v103 offset:56368
	s_waitcnt lgkmcnt(11)
	v_fmac_f32_e32 v49, v56, v144
	v_fmac_f32_e32 v48, v56, v145
	v_fmac_f32_e32 v46, v56, v146
	v_fmac_f32_e32 v43, v56, v147
	s_waitcnt lgkmcnt(10)
	v_fmac_f32_e32 v42, v56, v140
	v_fmac_f32_e32 v40, v56, v141
	v_fmac_f32_e32 v38, v56, v142
	v_fmac_f32_e32 v35, v56, v143
	s_waitcnt lgkmcnt(9)
	v_fmac_f32_e32 v51, v56, v148
	v_fmac_f32_e32 v50, v56, v149
	v_fmac_f32_e32 v47, v56, v150
	v_fmac_f32_e32 v45, v56, v151
	s_waitcnt lgkmcnt(8)
	v_fmac_f32_e32 v44, v56, v156
	v_fmac_f32_e32 v41, v56, v157
	v_fmac_f32_e32 v39, v56, v158
	v_fmac_f32_e32 v32, v56, v159
	ds_read_b128 v[226:229], v112
	ds_read_b128 v[196:199], v113
	ds_read_b128 v[230:233], v114
	ds_read_b128 v[234:237], v115
	s_waitcnt lgkmcnt(11)
	v_fmac_f32_e32 v49, v57, v152
	v_fmac_f32_e32 v48, v57, v153
	v_fmac_f32_e32 v46, v57, v154
	v_fmac_f32_e32 v43, v57, v155
	s_waitcnt lgkmcnt(10)
	v_fmac_f32_e32 v42, v57, v170
	v_fmac_f32_e32 v40, v57, v171
	v_fmac_f32_e32 v38, v57, v172
	v_fmac_f32_e32 v35, v57, v173
	s_waitcnt lgkmcnt(7)
	v_fmac_f32_e32 v49, v18, v178
	v_fmac_f32_e32 v48, v18, v179
	v_fmac_f32_e32 v46, v18, v180
	v_fmac_f32_e32 v43, v18, v181
	v_fmac_f32_e32 v51, v57, v188
	v_fmac_f32_e32 v50, v57, v189
	v_fmac_f32_e32 v47, v57, v190
	v_fmac_f32_e32 v45, v57, v191
	s_waitcnt lgkmcnt(6)
	v_fmac_f32_e32 v42, v18, v174
	v_fmac_f32_e32 v40, v18, v175
	v_fmac_f32_e32 v38, v18, v176
	v_fmac_f32_e32 v35, v18, v177
	v_fmac_f32_e32 v44, v57, v182
	v_fmac_f32_e32 v41, v57, v183
	v_fmac_f32_e32 v39, v57, v184
	v_fmac_f32_e32 v32, v57, v185
	s_waitcnt lgkmcnt(5)
	v_fmac_f32_e32 v51, v18, v222
	v_fmac_f32_e32 v50, v18, v223
	v_fmac_f32_e32 v47, v18, v224
	v_fmac_f32_e32 v45, v18, v225
	s_waitcnt lgkmcnt(4)
	v_fmac_f32_e32 v44, v18, v192
	v_fmac_f32_e32 v41, v18, v193
	v_fmac_f32_e32 v39, v18, v194
	v_fmac_f32_e32 v32, v18, v195
	s_waitcnt lgkmcnt(3)
	v_fmac_f32_e32 v49, v19, v226
	v_fmac_f32_e32 v48, v19, v227
	v_fmac_f32_e32 v46, v19, v228
	v_fmac_f32_e32 v43, v19, v229
	s_waitcnt lgkmcnt(2)
	v_fmac_f32_e32 v42, v19, v196
	v_fmac_f32_e32 v40, v19, v197
	v_fmac_f32_e32 v38, v19, v198
	v_fmac_f32_e32 v35, v19, v199
	s_waitcnt lgkmcnt(1)
	v_fmac_f32_e32 v51, v19, v230
	v_fmac_f32_e32 v50, v19, v231
	v_fmac_f32_e32 v47, v19, v232
	v_fmac_f32_e32 v45, v19, v233
	s_waitcnt lgkmcnt(0)
	v_fmac_f32_e32 v44, v19, v234
	v_fmac_f32_e32 v41, v19, v235
	v_fmac_f32_e32 v39, v19, v236
	v_fmac_f32_e32 v32, v19, v237
	v_cndmask_b32_e32 v140, v49, v51, vcc
	v_cndmask_b32_e32 v141, v51, v49, vcc
	v_cndmask_b32_e32 v142, v48, v50, vcc
	v_cndmask_b32_e32 v143, v50, v48, vcc
	v_cndmask_b32_e32 v144, v47, v46, vcc
	v_cndmask_b32_e32 v145, v45, v43, vcc
	v_cndmask_b32_e32 v146, v44, v42, vcc
	v_cndmask_b32_e32 v147, v46, v47, vcc
	v_cndmask_b32_e32 v148, v41, v40, vcc
	v_cndmask_b32_e32 v149, v39, v38, vcc
	v_cndmask_b32_e32 v150, v32, v35, vcc
	v_cndmask_b32_e32 v151, v43, v45, vcc
	v_cndmask_b32_e32 v152, v42, v44, vcc
	v_cndmask_b32_e32 v153, v40, v41, vcc
	v_cndmask_b32_e32 v154, v38, v39, vcc
	v_cndmask_b32_e32 v155, v35, v32, vcc
	ds_bpermute_b32 v156, v96, v140
	ds_bpermute_b32 v157, v96, v142
	ds_bpermute_b32 v158, v96, v147
	ds_bpermute_b32 v159, v96, v151
	ds_bpermute_b32 v170, v96, v152
	ds_bpermute_b32 v171, v96, v153
	ds_bpermute_b32 v172, v96, v154
	ds_bpermute_b32 v173, v96, v155
	s_waitcnt lgkmcnt(7)
	v_add_f32_e32 v174, v141, v156
	s_waitcnt lgkmcnt(6)
	v_add_f32_e32 v175, v143, v157
	s_waitcnt lgkmcnt(5)
	v_add_f32_e32 v176, v144, v158
	s_waitcnt lgkmcnt(4)
	v_add_f32_e32 v177, v145, v159
	s_waitcnt lgkmcnt(3)
	v_add_f32_e32 v178, v146, v170
	s_waitcnt lgkmcnt(2)
	v_add_f32_e32 v23, v148, v171
	s_waitcnt lgkmcnt(1)
	v_add_f32_e32 v24, v149, v172
	s_waitcnt lgkmcnt(0)
	v_add_f32_e32 v25, v150, v173
	v_cndmask_b32_e64 v26, v174, v178, s[42:43]
	v_cndmask_b32_e64 v179, v178, v174, s[42:43]
	v_cndmask_b32_e64 v180, v175, v23, s[42:43]
	v_cndmask_b32_e64 v181, v23, v175, s[42:43]
	v_cndmask_b32_e64 v182, v176, v24, s[42:43]
	v_cndmask_b32_e64 v183, v24, v176, s[42:43]
	v_cndmask_b32_e64 v184, v177, v25, s[42:43]
	v_cndmask_b32_e64 v185, v25, v177, s[42:43]
	ds_bpermute_b32 v188, v97, v26
	ds_bpermute_b32 v189, v97, v180
	ds_bpermute_b32 v190, v97, v182
	ds_bpermute_b32 v191, v97, v184
	s_waitcnt lgkmcnt(3)
	v_add_f32_e32 v192, v179, v188
	s_waitcnt lgkmcnt(2)
	v_add_f32_e32 v193, v181, v189
	s_waitcnt lgkmcnt(1)
	v_add_f32_e32 v194, v183, v190
	s_waitcnt lgkmcnt(0)
	v_add_f32_e32 v21, v185, v191
	v_cndmask_b32_e64 v22, v192, v194, s[44:45]
	v_cndmask_b32_e64 v195, v194, v192, s[44:45]
	v_cndmask_b32_e64 v196, v193, v21, s[44:45]
	v_cndmask_b32_e64 v197, v21, v193, s[44:45]
	ds_bpermute_b32 v198, v98, v22
	ds_bpermute_b32 v199, v98, v196
	s_waitcnt lgkmcnt(1)
	v_add_f32_e32 v222, v195, v198
	s_waitcnt lgkmcnt(0)
	v_add_f32_e32 v223, v197, v199
	v_cndmask_b32_e64 v20, v222, v223, s[46:47]
	v_cndmask_b32_e64 v224, v223, v222, s[46:47]
	ds_bpermute_b32 v225, v99, v20
	s_waitcnt lgkmcnt(0)
	v_add_f32_e32 v226, v224, v225
	ds_bpermute_b32 v227, v100, v226
	s_waitcnt lgkmcnt(0)
	v_add_f32_e32 v18, v226, v227
	ds_bpermute_b32 v19, v101, v18
	s_and_b64 exec, exec, s[48:49]
	s_cbranch_execz .LBB0_1045
; __device__ __forceinline__ float logsigmoidf_(float x) { return fminf(x, 0.0f) - log1pf(__expf(-fabsf(x))); }
; __device__ void phase0(const Params& P, LAS unsigned char* lds, const int G, const int bid) {
;     ...
;               r1 += __shfl_xor(r1, 2); r1 += __shfl_xor(r1, 1);
;               if ((lane & 3) == 0) { float gv = r1 + gbias; if (gcol >= 8) gv = logsigmoidf_(gv); gates[(size_t)row * 16 + gcol] = gv; }
	s_waitcnt lgkmcnt(0)
	v_add_f32_e32 v18, v18, v19
	v_add_f32_e32 v18, v91, v18
	s_and_saveexec_b64 s[8:9], s[40:41]
	s_cbranch_execz .LBB0_1044
	s_mov_b32 s12, 0xbfb8aa3b
	v_mul_f32_e64 v19, |v18|, s12
	v_exp_f32_e32 v32, v19
	v_max_f32_e32 v18, v18, v18
	v_min_f32_e32 v33, 0, v18
	s_mov_b32 s12, 0x3f2aaaab
	v_add_f32_e32 v20, 1.0, v32
	v_add_f32_e32 v18, -1.0, v20
	v_sub_f32_e32 v19, v18, v20
	v_sub_f32_e32 v18, v32, v18
	v_add_f32_e32 v19, 1.0, v19
	v_add_f32_e32 v21, v18, v19
	v_frexp_mant_f32_e32 v22, v20
	v_cvt_f64_f32_e32 v[18:19], v20
	v_frexp_exp_i32_f64_e32 v18, v[18:19]
	v_cmp_gt_f32_e64 s[50:51], s12, v22
	s_mov_b32 s12, 0x3f317218
	s_nop 0
	v_subbrev_co_u32_e64 v26, s[50:51], 0, v18, s[50:51]
	v_sub_u32_e32 v18, 0, v26
	v_ldexp_f32 v19, v20, v18
	v_add_f32_e32 v20, -1.0, v19
	v_add_f32_e32 v22, 1.0, v19
	v_ldexp_f32 v18, v21, v18
	v_add_f32_e32 v21, 1.0, v20
	v_add_f32_e32 v23, -1.0, v22
	v_sub_f32_e32 v21, v19, v21
	v_sub_f32_e32 v19, v19, v23
	v_add_f32_e32 v21, v18, v21
	v_add_f32_e32 v18, v18, v19
	v_add_f32_e32 v27, v22, v18
	v_rcp_f32_e32 v29, v27
	v_sub_f32_e32 v19, v27, v22
	v_sub_f32_e32 v28, v18, v19
	v_add_f32_e32 v19, v20, v21
	v_mul_f32_e32 v31, v19, v29
	v_sub_f32_e32 v18, v19, v20
	v_mul_f32_e32 v20, v27, v31
	v_fma_f32 v22, v31, v27, -v20
	v_fmac_f32_e32 v22, v31, v28
	v_sub_f32_e32 v30, v21, v18
	v_add_f32_e32 v18, v20, v22
	v_sub_f32_e32 v21, v19, v18
	v_pk_add_f32 v[24:25], v[18:19], v[20:21] neg_lo:[0,1] neg_hi:[0,1]
	v_mov_b32_e32 v23, v18
	v_pk_add_f32 v[18:19], v[24:25], v[22:23] neg_lo:[0,1] neg_hi:[0,1]
	s_nop 0
	v_add_f32_e32 v19, v30, v19
	v_add_f32_e32 v18, v18, v19
	v_add_f32_e32 v19, v21, v18
	v_mul_f32_e32 v30, v29, v19
	v_mul_f32_e32 v20, v27, v30
	v_fma_f32 v22, v30, v27, -v20
	v_fmac_f32_e32 v22, v30, v28
	v_sub_f32_e32 v21, v21, v19
	v_add_f32_e32 v27, v18, v21
	v_add_f32_e32 v18, v20, v22
	v_sub_f32_e32 v21, v19, v18
	v_pk_add_f32 v[24:25], v[18:19], v[20:21] neg_lo:[0,1] neg_hi:[0,1]
	v_mov_b32_e32 v23, v18
	v_pk_add_f32 v[18:19], v[24:25], v[22:23] neg_lo:[0,1] neg_hi:[0,1]
	s_nop 0
	v_add_f32_e32 v19, v27, v19
	v_add_f32_e32 v18, v18, v19
	v_add_f32_e32 v19, v31, v30
	v_add_f32_e32 v18, v21, v18
	v_sub_f32_e32 v20, v19, v31
	v_mul_f32_e32 v18, v29, v18
	v_sub_f32_e32 v20, v30, v20
	v_add_f32_e32 v20, v20, v18
	v_add_f32_e32 v22, v19, v20
	v_mul_f32_e32 v23, v22, v22
	v_fmamk_f32 v18, v23, 0x3e9b6dac, v208
	v_fmaak_f32 v169, v23, v18, 0x3f2aaada
	v_cvt_f32_i32_e32 v18, v26
	v_sub_f32_e32 v19, v22, v19
	v_sub_f32_e32 v19, v20, v19
	v_ldexp_f32 v24, v19, 1
	v_mul_f32_e32 v19, v22, v23
	v_ldexp_f32 v21, v22, 1
	v_pk_mul_f32 v[22:23], v[18:19], v[168:169]
	s_nop 0
	v_fma_f32 v20, v18, s12, -v22
	v_fmac_f32_e32 v20, 0xb102e308, v18
	v_pk_add_f32 v[18:19], v[22:23], v[20:21]
	s_mov_b32 s12, 0x7f800000
	v_sub_f32_e32 v21, v19, v21
	v_sub_f32_e32 v21, v23, v21
	v_add_f32_e32 v25, v24, v21
	v_mov_b32_e32 v24, v22
	v_pk_add_f32 v[22:23], v[18:19], v[22:23] neg_lo:[0,1] neg_hi:[0,1]
	v_pk_add_f32 v[26:27], v[18:19], v[24:25]
	v_mov_b32_e32 v21, v18
	v_mov_b32_e32 v23, v27
	v_pk_add_f32 v[28:29], v[20:21], v[22:23] neg_lo:[0,1] neg_hi:[0,1]
	v_pk_add_f32 v[20:21], v[20:21], v[22:23]
	v_mov_b32_e32 v24, v25
	v_pk_add_f32 v[22:23], v[20:21], v[18:19] op_sel:[1,0] op_sel_hi:[0,1] neg_lo:[0,1] neg_hi:[0,1]
	s_nop 0
	v_pk_add_f32 v[30:31], v[26:27], v[22:23] op_sel_hi:[1,0] neg_lo:[0,1] neg_hi:[0,1]
	v_mov_b32_e32 v26, v27
	v_mov_b32_e32 v27, v21
	v_pk_mov_b32 v[22:23], v[18:19], v[22:23] op_sel:[1,0]
	v_mov_b32_e32 v25, v18
	v_pk_add_f32 v[22:23], v[26:27], v[22:23] neg_lo:[0,1] neg_hi:[0,1]
	v_mov_b32_e32 v30, v28
	v_pk_add_f32 v[18:19], v[24:25], v[22:23] neg_lo:[0,1] neg_hi:[0,1]
	v_mov_b32_e32 v29, v21
	v_pk_add_f32 v[22:23], v[30:31], v[18:19]
	v_cmp_neq_f32_e64 s[50:51], s12, v32
	v_pk_add_f32 v[24:25], v[22:23], v[22:23] op_sel:[0,1] op_sel_hi:[1,0]
	s_mov_b32 s12, 0x33800000
	v_pk_add_f32 v[20:21], v[20:21], v[24:25] op_sel:[1,0] op_sel_hi:[0,1]
	s_nop 0
	v_mov_b32_e32 v23, v20
	v_pk_add_f32 v[26:27], v[22:23], v[28:29] neg_lo:[0,1] neg_hi:[0,1]
	v_mov_b32_e32 v19, v24
	v_sub_f32_e32 v21, v22, v26
	v_pk_add_f32 v[18:19], v[18:19], v[26:27] neg_lo:[0,1] neg_hi:[0,1]
	v_sub_f32_e32 v21, v28, v21
	v_add_f32_e32 v18, v18, v21
	v_add_f32_e32 v18, v18, v19
	v_add_f32_e32 v18, v20, v18
	v_cndmask_b32_e64 v18, v212, v18, s[50:51]
	v_cmp_ngt_f32_e64 s[50:51], -1.0, v32
	s_nop 1
	v_cndmask_b32_e64 v18, v213, v18, s[50:51]
	v_cmp_neq_f32_e64 s[50:51], -1.0, v32
	s_nop 1
	v_cndmask_b32_e64 v18, v214, v18, s[50:51]
	v_cmp_lt_f32_e64 s[50:51], |v32|, s12
	s_nop 1
	v_cndmask_b32_e64 v18, v18, v32, s[50:51]
	v_sub_f32_e32 v18, v33, v18
	s_branch .LBB0_1044
